# adds: RMSNorm gain vectors loaded once before the row loops (P6/P10/P12); P8 conv row loop unrolled x2 with the row two ahead in flight
# baseline (speedup 1.0000x reference)
; __device__ __forceinline__ unsigned pk2(float lo, float hi) { const f32x2 v = {lo, hi}; const hwbf16x2 r = __builtin_convertvector(v, hwbf16x2); return __builtin_bit_cast(unsigned, r); }
; __device__ __forceinline__ float bf_lo(unsigned v) { return __uint_as_float(v << 16); }
; __device__ __forceinline__ float bf_hi(unsigned v) { return __uint_as_float(v & 0xffff0000u); }
; __device__ __forceinline__ void rms_rowb_to_bf16(const bf16* hrow, const float* w, bf16* orow, int lane) {
;     const v4u* hr = (const v4u*)hrow + lane; float v[8][8]; float s = 0.f;
; #pragma unroll
;     for (int j = 0; j < 8; ++j) { const v4u q = hr[64 * j];
;         v[j][0] = bf_lo(q.x); v[j][1] = bf_hi(q.x); v[j][2] = bf_lo(q.y); v[j][3] = bf_hi(q.y); v[j][4] = bf_lo(q.z); v[j][5] = bf_hi(q.z); v[j][6] = bf_lo(q.w); v[j][7] = bf_hi(q.w);
; #pragma unroll
;         for (int e = 0; e < 8; ++e) s += v[j][e] * v[j][e]; }
;     const float r = rsqrtf(wave_sum(s) * (1.f / D) + EPS);
;     v4u* o = (v4u*)orow + lane;
; #pragma unroll
;     for (int j = 0; j < 8; ++j) { const f32x4 g0 = *(const f32x4*)(w + (64 * j + lane) * 8), g1 = *(const f32x4*)(w + (64 * j + lane) * 8 + 4);
;         v4u q; q.x = pk2(v[j][0] * r * g0.x, v[j][1] * r * g0.y); q.y = pk2(v[j][2] * r * g0.z, v[j][3] * r * g0.w); q.z = pk2(v[j][4] * r * g1.x, v[j][5] * r * g1.y); q.w = pk2(v[j][6] * r * g1.z, v[j][7] * r * g1.w);
;         o[64 * j] = q; }
.LBB0_741:
	s_cmp_lt_i32 s30, 7
	s_cselect_b64 s[4:5], -1, 0
	s_and_b64 s[0:1], s[4:5], s[6:7]
	s_cmpk_lt_i32 s92, 0x2000
	s_cselect_b64 s[10:11], -1, 0
	s_and_b64 s[0:1], s[0:1], s[10:11]
	s_andn2_b64 vcc, exec, s[0:1]
	v_lshlrev_b32_e32 v144, 5, v165
	v_lshlrev_b32_e32 v146, 4, v165
	s_cbranch_vccnz .LBB0_744
	s_waitcnt vmcnt(0)
	v_mbcnt_hi_u32_b32 v0, -1, v168
	v_and_b32_e32 v1, 64, v0
	v_add_u32_e32 v1, 64, v1
	v_xor_b32_e32 v2, 1, v0
	v_cmp_lt_i32_e32 vcc, v2, v1
	v_readlane_b32 s36, v253, 6
	v_mov_b32_e32 v145, 0
	v_cndmask_b32_e32 v2, v0, v2, vcc
	v_lshlrev_b32_e32 v60, 2, v2
	v_xor_b32_e32 v2, 2, v0
	v_cmp_lt_i32_e32 vcc, v2, v1
	v_readlane_b32 s38, v253, 8
	v_readlane_b32 s39, v253, 9
	v_cndmask_b32_e32 v2, v0, v2, vcc
	v_lshlrev_b32_e32 v61, 2, v2
	v_xor_b32_e32 v2, 4, v0
	v_cmp_lt_i32_e32 vcc, v2, v1
	v_lshl_add_u64 v[24:25], s[38:39], 0, v[144:145]
	s_mov_b64 s[0:1], 0x1000
	v_cndmask_b32_e32 v2, v0, v2, vcc
	v_lshlrev_b32_e32 v62, 2, v2
	v_xor_b32_e32 v2, 8, v0
	v_cmp_lt_i32_e32 vcc, v2, v1
	v_lshl_add_u64 v[26:27], v[24:25], 0, s[0:1]
	s_mov_b64 s[0:1], 0x1800
	v_cndmask_b32_e32 v2, v0, v2, vcc
	v_lshl_add_u64 v[28:29], v[24:25], 0, s[0:1]
	s_mov_b64 s[0:1], 0x2000
	v_lshlrev_b32_e32 v63, 2, v2
	v_xor_b32_e32 v2, 16, v0
	v_lshl_add_u64 v[30:31], v[24:25], 0, s[0:1]
	s_mov_b64 s[0:1], 0x2800
	v_cmp_lt_i32_e32 vcc, v2, v1
	v_lshl_add_u64 v[32:33], v[24:25], 0, s[0:1]
	s_mov_b64 s[0:1], 0x3000
	v_cndmask_b32_e32 v2, v0, v2, vcc
	v_lshl_add_u64 v[34:35], v[24:25], 0, s[0:1]
	s_mov_b64 s[0:1], 0x3800
	s_ashr_i32 s93, s92, 31
	v_lshlrev_b32_e32 v64, 2, v2
	v_xor_b32_e32 v2, 32, v0
	v_lshl_add_u64 v[36:37], v[24:25], 0, s[0:1]
	s_lshl_b64 s[0:1], s[92:93], 13
	v_cmp_lt_i32_e32 vcc, v2, v1
	s_add_u32 s0, s28, s0
	v_mov_b32_e32 v147, v145
	v_cndmask_b32_e32 v0, v0, v2, vcc
	s_addc_u32 s1, s29, s1
	v_lshlrev_b32_e32 v65, 2, v0
	v_lshl_add_u64 v[0:1], s[0:1], 0, v[146:147]
	s_mov_b64 s[0:1], 0x1c801c00
	s_ashr_i32 s95, s94, 31
	v_lshl_add_u64 v[38:39], v[0:1], 0, s[0:1]
	s_lshl_b64 s[6:7], s[94:95], 13
	v_mov_b32_e32 v66, 0x358637bd
	s_mov_b32 s12, 0x800000
	s_mov_b32 s13, 0xfbfff000
	s_brev_b32 s14, 63
	s_mov_b32 s15, s92
	v_readlane_b32 s37, v253, 7
	v_readlane_b32 s40, v253, 10
	v_readlane_b32 s41, v253, 11
	v_readlane_b32 s42, v253, 12
	v_readlane_b32 s43, v253, 13
	v_readlane_b32 s44, v253, 14
	v_readlane_b32 s45, v253, 15
	v_readlane_b32 s46, v253, 16
	v_readlane_b32 s47, v253, 17
	v_readlane_b32 s48, v253, 18
	v_readlane_b32 s49, v253, 19
	v_readlane_b32 s50, v253, 20
	v_readlane_b32 s51, v253, 21
	global_load_dwordx4 v[172:175], v[24:25], off offset:16
	global_load_dwordx4 v[176:179], v[24:25], off
	global_load_dwordx4 v[180:183], v[24:25], off offset:2048
	global_load_dwordx4 v[184:187], v[24:25], off offset:2064
	global_load_dwordx4 v[188:191], v[26:27], off
	global_load_dwordx4 v[192:195], v[26:27], off offset:16
	global_load_dwordx4 v[196:199], v[28:29], off
	global_load_dwordx4 v[200:203], v[28:29], off offset:16
	global_load_dwordx4 v[204:207], v[30:31], off
	global_load_dwordx4 v[208:211], v[30:31], off offset:16
	global_load_dwordx4 v[212:215], v[32:33], off
	global_load_dwordx4 v[216:219], v[32:33], off offset:16
	global_load_dwordx4 v[220:223], v[34:35], off
	global_load_dwordx4 v[224:227], v[34:35], off offset:16
	global_load_dwordx4 v[228:231], v[36:37], off
	global_load_dwordx4 v[232:235], v[36:37], off offset:16
.LBB0_743:
	v_add_co_u32_e32 v40, vcc, 0xfffff000, v38
	global_load_dwordx4 v[20:23], v[38:39], off offset:-3072
	global_load_dwordx4 v[16:19], v[38:39], off offset:-2048
	global_load_dwordx4 v[12:15], v[38:39], off offset:-1024
	global_load_dwordx4 v[8:11], v[38:39], off
	v_addc_co_u32_e32 v41, vcc, -1, v39, vcc
	global_load_dwordx4 v[68:71], v[40:41], off offset:-3072
	global_load_dwordx4 v[72:75], v[40:41], off offset:-2048
	global_load_dwordx4 v[76:79], v[40:41], off offset:-1024
	global_load_dwordx4 v[80:83], v[38:39], off offset:-4096
	v_add_co_u32_e64 v58, s[0:1], s13, v38
	s_add_i32 s15, s15, s94
	s_nop 0
	v_addc_co_u32_e64 v59, s[0:1], -1, v39, s[0:1]
	s_cmpk_lt_i32 s15, 0x2000
	s_waitcnt vmcnt(7)
	v_lshlrev_b32_e32 v56, 16, v20
	v_and_b32_e32 v57, 0xffff0000, v20
	v_pk_mul_f32 v[88:89], v[56:57], v[56:57]
	v_lshlrev_b32_e32 v54, 16, v21
	s_waitcnt vmcnt(3)
	v_lshlrev_b32_e32 v118, 16, v68
	v_and_b32_e32 v119, 0xffff0000, v68
	v_lshlrev_b32_e32 v114, 16, v71
	v_and_b32_e32 v115, 0xffff0000, v71
	v_lshlrev_b32_e32 v116, 16, v70
	v_and_b32_e32 v117, 0xffff0000, v70
	v_lshlrev_b32_e32 v70, 16, v69
	v_and_b32_e32 v71, 0xffff0000, v69
	v_pk_mul_f32 v[136:137], v[118:119], v[118:119]
	v_pk_mul_f32 v[134:135], v[70:71], v[70:71]
	v_add_f32_e32 v67, v136, v137
	v_add_f32_e32 v67, v134, v67
	v_pk_mul_f32 v[132:133], v[116:117], v[116:117]
	v_add_f32_e32 v67, v135, v67
	v_add_f32_e32 v67, v132, v67
	s_waitcnt vmcnt(2)
	v_lshlrev_b32_e32 v68, 16, v75
	v_and_b32_e32 v69, 0xffff0000, v75
	v_lshlrev_b32_e32 v120, 16, v74
	v_and_b32_e32 v121, 0xffff0000, v74
	v_lshlrev_b32_e32 v74, 16, v73
	v_and_b32_e32 v75, 0xffff0000, v73
	v_lshlrev_b32_e32 v122, 16, v72
	v_and_b32_e32 v123, 0xffff0000, v72
	s_waitcnt vmcnt(1)
	v_lshlrev_b32_e32 v72, 16, v79
	v_and_b32_e32 v73, 0xffff0000, v79
	v_lshlrev_b32_e32 v124, 16, v78
	v_and_b32_e32 v125, 0xffff0000, v78
	v_lshlrev_b32_e32 v78, 16, v77
	v_and_b32_e32 v79, 0xffff0000, v77
	v_lshlrev_b32_e32 v126, 16, v76
	v_and_b32_e32 v127, 0xffff0000, v76
	s_waitcnt vmcnt(0)
; __device__ __forceinline__ float bf_lo(unsigned v) { return __uint_as_float(v << 16); }
; __device__ __forceinline__ float bf_hi(unsigned v) { return __uint_as_float(v & 0xffff0000u); }
; __device__ __forceinline__ void rms_rowb_to_bf16(const bf16* hrow, const float* w, bf16* orow, int lane) {
;     const v4u* hr = (const v4u*)hrow + lane; float v[8][8]; float s = 0.f;
; #pragma unroll
;     for (int j = 0; j < 8; ++j) { const v4u q = hr[64 * j];
;         v[j][0] = bf_lo(q.x); v[j][1] = bf_hi(q.x); v[j][2] = bf_lo(q.y); v[j][3] = bf_hi(q.y); v[j][4] = bf_lo(q.z); v[j][5] = bf_hi(q.z); v[j][6] = bf_lo(q.w); v[j][7] = bf_hi(q.w);
; #pragma unroll
;         for (int e = 0; e < 8; ++e) s += v[j][e] * v[j][e]; }
;     const float r = rsqrtf(wave_sum(s) * (1.f / D) + EPS);
	v_lshlrev_b32_e32 v76, 16, v83
	v_and_b32_e32 v77, 0xffff0000, v83
	v_lshlrev_b32_e32 v128, 16, v82
	v_and_b32_e32 v129, 0xffff0000, v82
	v_lshlrev_b32_e32 v82, 16, v81
	v_and_b32_e32 v83, 0xffff0000, v81
	v_lshlrev_b32_e32 v130, 16, v80
	v_and_b32_e32 v131, 0xffff0000, v80
	v_pk_mul_f32 v[80:81], v[114:115], v[114:115]
	v_add_f32_e32 v67, v133, v67
	v_add_f32_e32 v67, v80, v67
	v_pk_mul_f32 v[152:153], v[122:123], v[122:123]
	v_add_f32_e32 v67, v81, v67
	v_add_f32_e32 v67, v152, v67
	v_pk_mul_f32 v[150:151], v[74:75], v[74:75]
	v_add_f32_e32 v67, v153, v67
	v_add_f32_e32 v67, v150, v67
	v_pk_mul_f32 v[148:149], v[120:121], v[120:121]
	v_add_f32_e32 v67, v151, v67
	v_add_f32_e32 v67, v148, v67
	v_pk_mul_f32 v[138:139], v[68:69], v[68:69]
	v_add_f32_e32 v67, v149, v67
	v_add_f32_e32 v67, v138, v67
	v_pk_mul_f32 v[160:161], v[126:127], v[126:127]
	v_add_f32_e32 v67, v139, v67
	v_add_f32_e32 v67, v160, v67
	v_pk_mul_f32 v[158:159], v[78:79], v[78:79]
	v_add_f32_e32 v67, v161, v67
	v_add_f32_e32 v67, v158, v67
	v_pk_mul_f32 v[156:157], v[124:125], v[124:125]
	v_add_f32_e32 v67, v159, v67
	v_add_f32_e32 v67, v156, v67
	v_pk_mul_f32 v[154:155], v[72:73], v[72:73]
	v_add_f32_e32 v67, v157, v67
	v_add_f32_e32 v67, v154, v67
	v_pk_mul_f32 v[170:171], v[130:131], v[130:131]
	v_add_f32_e32 v67, v155, v67
	v_add_f32_e32 v67, v170, v67
	v_pk_mul_f32 v[166:167], v[82:83], v[82:83]
	v_add_f32_e32 v67, v171, v67
	v_add_f32_e32 v67, v166, v67
	v_pk_mul_f32 v[164:165], v[128:129], v[128:129]
	v_add_f32_e32 v67, v167, v67
	v_add_f32_e32 v67, v164, v67
	v_pk_mul_f32 v[162:163], v[76:77], v[76:77]
	v_add_f32_e32 v67, v165, v67
	v_add_f32_e32 v67, v162, v67
	v_add_f32_e32 v67, v163, v67
	v_and_b32_e32 v55, 0xffff0000, v21
	v_add_f32_e32 v67, v88, v67
	v_pk_mul_f32 v[86:87], v[54:55], v[54:55]
	v_add_f32_e32 v67, v89, v67
	v_lshlrev_b32_e32 v52, 16, v22
	v_and_b32_e32 v53, 0xffff0000, v22
	v_add_f32_e32 v67, v86, v67
	v_pk_mul_f32 v[84:85], v[52:53], v[52:53]
	v_add_f32_e32 v67, v87, v67
	v_lshlrev_b32_e32 v50, 16, v23
	v_and_b32_e32 v51, 0xffff0000, v23
	v_add_f32_e32 v67, v84, v67
	v_lshlrev_b32_e32 v42, 16, v19
	v_and_b32_e32 v43, 0xffff0000, v19
	v_lshlrev_b32_e32 v44, 16, v18
	v_and_b32_e32 v45, 0xffff0000, v18
	v_lshlrev_b32_e32 v46, 16, v17
	v_and_b32_e32 v47, 0xffff0000, v17
	v_lshlrev_b32_e32 v48, 16, v16
	v_and_b32_e32 v49, 0xffff0000, v16
	v_lshlrev_b32_e32 v18, 16, v15
	v_and_b32_e32 v19, 0xffff0000, v15
	v_lshlrev_b32_e32 v20, 16, v14
	v_and_b32_e32 v21, 0xffff0000, v14
	v_lshlrev_b32_e32 v22, 16, v13
	v_and_b32_e32 v23, 0xffff0000, v13
	v_lshlrev_b32_e32 v40, 16, v12
	v_and_b32_e32 v41, 0xffff0000, v12
	v_lshlrev_b32_e32 v12, 16, v11
	v_and_b32_e32 v13, 0xffff0000, v11
	v_lshlrev_b32_e32 v14, 16, v10
	v_and_b32_e32 v15, 0xffff0000, v10
	v_lshlrev_b32_e32 v10, 16, v9
	v_and_b32_e32 v11, 0xffff0000, v9
	v_lshlrev_b32_e32 v16, 16, v8
	v_and_b32_e32 v17, 0xffff0000, v8
	v_pk_mul_f32 v[8:9], v[50:51], v[50:51]
	v_add_f32_e32 v67, v85, v67
	v_add_f32_e32 v8, v8, v67
	v_pk_mul_f32 v[96:97], v[48:49], v[48:49]
	v_add_f32_e32 v8, v9, v8
	v_add_f32_e32 v8, v96, v8
	v_pk_mul_f32 v[94:95], v[46:47], v[46:47]
	v_add_f32_e32 v8, v97, v8
	v_add_f32_e32 v8, v94, v8
	v_pk_mul_f32 v[92:93], v[44:45], v[44:45]
	v_add_f32_e32 v8, v95, v8
	v_add_f32_e32 v8, v92, v8
	v_pk_mul_f32 v[90:91], v[42:43], v[42:43]
	v_add_f32_e32 v8, v93, v8
	v_add_f32_e32 v8, v90, v8
	v_pk_mul_f32 v[104:105], v[40:41], v[40:41]
	v_add_f32_e32 v8, v91, v8
	v_add_f32_e32 v8, v104, v8
	v_pk_mul_f32 v[102:103], v[22:23], v[22:23]
	v_add_f32_e32 v8, v105, v8
	v_add_f32_e32 v8, v102, v8
	v_pk_mul_f32 v[100:101], v[20:21], v[20:21]
	v_add_f32_e32 v8, v103, v8
	v_add_f32_e32 v8, v100, v8
	v_pk_mul_f32 v[98:99], v[18:19], v[18:19]
	v_add_f32_e32 v8, v101, v8
	v_add_f32_e32 v8, v98, v8
	v_pk_mul_f32 v[112:113], v[16:17], v[16:17]
	v_add_f32_e32 v8, v99, v8
	v_add_f32_e32 v8, v112, v8
	v_pk_mul_f32 v[110:111], v[10:11], v[10:11]
	v_add_f32_e32 v8, v113, v8
	v_add_f32_e32 v8, v110, v8
	v_pk_mul_f32 v[108:109], v[14:15], v[14:15]
	v_add_f32_e32 v8, v111, v8
	v_add_f32_e32 v8, v108, v8
	v_pk_mul_f32 v[106:107], v[12:13], v[12:13]
	v_add_f32_e32 v8, v109, v8
	v_add_f32_e32 v8, v106, v8
	v_add_f32_e32 v8, v107, v8
	ds_bpermute_b32 v9, v60, v8
	s_waitcnt lgkmcnt(0)
	v_add_f32_e32 v8, v8, v9
	ds_bpermute_b32 v9, v61, v8
	s_waitcnt lgkmcnt(0)
	v_add_f32_e32 v8, v8, v9
	ds_bpermute_b32 v9, v62, v8
	s_waitcnt lgkmcnt(0)
	v_add_f32_e32 v8, v8, v9
	ds_bpermute_b32 v9, v63, v8
	s_waitcnt lgkmcnt(0)
	v_add_f32_e32 v8, v8, v9
	ds_bpermute_b32 v9, v64, v8
	s_waitcnt lgkmcnt(0)
	v_add_f32_e32 v8, v8, v9
	ds_bpermute_b32 v9, v65, v8
	s_waitcnt lgkmcnt(0)
; __device__ __forceinline__ unsigned pk2(float lo, float hi) { const f32x2 v = {lo, hi}; const hwbf16x2 r = __builtin_convertvector(v, hwbf16x2); return __builtin_bit_cast(unsigned, r); }
; __device__ __forceinline__ void rms_rowb_to_bf16(const bf16* hrow, const float* w, bf16* orow, int lane) {
;     ...
;     const float r = rsqrtf(wave_sum(s) * (1.f / D) + EPS);
;     v4u* o = (v4u*)orow + lane;
; #pragma unroll
;     for (int j = 0; j < 8; ++j) { const f32x4 g0 = *(const f32x4*)(w + (64 * j + lane) * 8), g1 = *(const f32x4*)(w + (64 * j + lane) * 8 + 4);
;         v4u q; q.x = pk2(v[j][0] * r * g0.x, v[j][1] * r * g0.y); q.y = pk2(v[j][2] * r * g0.z, v[j][3] * r * g0.w); q.z = pk2(v[j][4] * r * g1.x, v[j][5] * r * g1.y); q.w = pk2(v[j][6] * r * g1.z, v[j][7] * r * g1.w);
;         o[64 * j] = q; }
	v_add_f32_e32 v8, v8, v9
	v_fmamk_f32 v8, v8, 0x39800000, v66
	v_mul_f32_e32 v9, 0x4b800000, v8
	v_cmp_gt_f32_e32 vcc, s12, v8
	s_nop 1
	v_cndmask_b32_e32 v8, v8, v9, vcc
	v_rsq_f32_e32 v8, v8
	s_nop 0
	v_mul_f32_e32 v9, 0x45800000, v8
	v_cndmask_b32_e32 v8, v8, v9, vcc
	v_pk_mul_f32 v[80:81], v[8:9], v[118:119] op_sel_hi:[0,1]
	v_pk_mul_f32 v[70:71], v[8:9], v[70:71] op_sel_hi:[0,1]
	v_pk_mul_f32 v[84:85], v[8:9], v[116:117] op_sel_hi:[0,1]
	v_pk_mul_f32 v[86:87], v[8:9], v[114:115] op_sel_hi:[0,1]
	v_pk_mul_f32 v[4:5], v[176:177], v[80:81]
	v_pk_mul_f32 v[6:7], v[178:179], v[70:71]
	v_pk_mul_f32 v[70:71], v[172:173], v[84:85]
	v_pk_mul_f32 v[80:81], v[174:175], v[86:87]
	v_cvt_pk_bf16_f32 v0, v4, v5
	v_cvt_pk_bf16_f32 v1, v6, v7
	v_cvt_pk_bf16_f32 v2, v70, v71
	v_cvt_pk_bf16_f32 v3, v80, v81
	global_store_dwordx4 v[58:59], v[0:3], off offset:-3072
	s_nop 1
	s_nop 0
	v_pk_mul_f32 v[70:71], v[8:9], v[122:123] op_sel_hi:[0,1]
	v_pk_mul_f32 v[74:75], v[8:9], v[74:75] op_sel_hi:[0,1]
	v_pk_mul_f32 v[80:81], v[8:9], v[120:121] op_sel_hi:[0,1]
	v_pk_mul_f32 v[68:69], v[8:9], v[68:69] op_sel_hi:[0,1]
	v_pk_mul_f32 v[72:73], v[8:9], v[72:73] op_sel_hi:[0,1]
	v_pk_mul_f32 v[56:57], v[8:9], v[56:57] op_sel_hi:[0,1]
	v_pk_mul_f32 v[54:55], v[8:9], v[54:55] op_sel_hi:[0,1]
	v_pk_mul_f32 v[52:53], v[8:9], v[52:53] op_sel_hi:[0,1]
	v_pk_mul_f32 v[50:51], v[8:9], v[50:51] op_sel_hi:[0,1]
	v_pk_mul_f32 v[48:49], v[8:9], v[48:49] op_sel_hi:[0,1]
	v_pk_mul_f32 v[46:47], v[8:9], v[46:47] op_sel_hi:[0,1]
	v_pk_mul_f32 v[44:45], v[8:9], v[44:45] op_sel_hi:[0,1]
	v_pk_mul_f32 v[42:43], v[8:9], v[42:43] op_sel_hi:[0,1]
	v_pk_mul_f32 v[40:41], v[8:9], v[40:41] op_sel_hi:[0,1]
	v_pk_mul_f32 v[22:23], v[8:9], v[22:23] op_sel_hi:[0,1]
	v_pk_mul_f32 v[20:21], v[8:9], v[20:21] op_sel_hi:[0,1]
	v_pk_mul_f32 v[18:19], v[8:9], v[18:19] op_sel_hi:[0,1]
	v_pk_mul_f32 v[16:17], v[8:9], v[16:17] op_sel_hi:[0,1]
	v_pk_mul_f32 v[10:11], v[8:9], v[10:11] op_sel_hi:[0,1]
	v_pk_mul_f32 v[14:15], v[8:9], v[14:15] op_sel_hi:[0,1]
	v_pk_mul_f32 v[0:1], v[180:181], v[70:71]
	v_pk_mul_f32 v[2:3], v[182:183], v[74:75]
	v_pk_mul_f32 v[4:5], v[184:185], v[80:81]
	v_pk_mul_f32 v[6:7], v[186:187], v[68:69]
	v_cvt_pk_bf16_f32 v0, v0, v1
	v_cvt_pk_bf16_f32 v1, v2, v3
	v_cvt_pk_bf16_f32 v2, v4, v5
	v_cvt_pk_bf16_f32 v3, v6, v7
	global_store_dwordx4 v[58:59], v[0:3], off offset:-2048
	s_nop 1
	s_nop 0
	v_pk_mul_f32 v[68:69], v[8:9], v[126:127] op_sel_hi:[0,1]
	v_pk_mul_f32 v[70:71], v[8:9], v[78:79] op_sel_hi:[0,1]
	v_pk_mul_f32 v[74:75], v[8:9], v[124:125] op_sel_hi:[0,1]
	v_pk_mul_f32 v[0:1], v[188:189], v[68:69]
	v_pk_mul_f32 v[2:3], v[190:191], v[70:71]
	v_pk_mul_f32 v[4:5], v[192:193], v[74:75]
	v_pk_mul_f32 v[6:7], v[194:195], v[72:73]
	v_cvt_pk_bf16_f32 v0, v0, v1
	v_cvt_pk_bf16_f32 v1, v2, v3
	v_cvt_pk_bf16_f32 v2, v4, v5
	v_cvt_pk_bf16_f32 v3, v6, v7
	global_store_dwordx4 v[58:59], v[0:3], off offset:-1024
	s_nop 1
	s_nop 0
	v_pk_mul_f32 v[68:69], v[8:9], v[130:131] op_sel_hi:[0,1]
	v_pk_mul_f32 v[70:71], v[8:9], v[82:83] op_sel_hi:[0,1]
	v_pk_mul_f32 v[72:73], v[8:9], v[128:129] op_sel_hi:[0,1]
	v_pk_mul_f32 v[74:75], v[8:9], v[76:77] op_sel_hi:[0,1]
	v_add_co_u32_e32 v58, vcc, s14, v38
	v_pk_mul_f32 v[8:9], v[8:9], v[12:13] op_sel_hi:[0,1]
	s_nop 0
	v_addc_co_u32_e32 v59, vcc, -1, v39, vcc
	v_lshl_add_u64 v[38:39], v[38:39], 0, s[6:7]
	v_pk_mul_f32 v[0:1], v[196:197], v[68:69]
	v_pk_mul_f32 v[2:3], v[198:199], v[70:71]
	v_pk_mul_f32 v[4:5], v[200:201], v[72:73]
	v_pk_mul_f32 v[6:7], v[202:203], v[74:75]
	v_cvt_pk_bf16_f32 v0, v0, v1
	v_cvt_pk_bf16_f32 v1, v2, v3
	v_cvt_pk_bf16_f32 v2, v4, v5
	v_cvt_pk_bf16_f32 v3, v6, v7
	global_store_dwordx4 v[58:59], v[0:3], off offset:-4096
	s_nop 1
	s_nop 0
	v_pk_mul_f32 v[0:1], v[204:205], v[56:57]
	v_pk_mul_f32 v[2:3], v[206:207], v[54:55]
	v_pk_mul_f32 v[4:5], v[208:209], v[52:53]
	v_pk_mul_f32 v[6:7], v[210:211], v[50:51]
	v_cvt_pk_bf16_f32 v0, v0, v1
	v_cvt_pk_bf16_f32 v1, v2, v3
	v_cvt_pk_bf16_f32 v2, v4, v5
	v_cvt_pk_bf16_f32 v3, v6, v7
	global_store_dwordx4 v[58:59], v[0:3], off offset:-3072
	s_nop 1
	s_nop 0
	v_pk_mul_f32 v[0:1], v[212:213], v[48:49]
	v_pk_mul_f32 v[2:3], v[214:215], v[46:47]
	v_pk_mul_f32 v[4:5], v[216:217], v[44:45]
	v_pk_mul_f32 v[6:7], v[218:219], v[42:43]
	v_cvt_pk_bf16_f32 v0, v0, v1
	v_cvt_pk_bf16_f32 v1, v2, v3
	v_cvt_pk_bf16_f32 v2, v4, v5
	v_cvt_pk_bf16_f32 v3, v6, v7
	global_store_dwordx4 v[58:59], v[0:3], off offset:-2048
	s_nop 1
	s_nop 0
	v_pk_mul_f32 v[0:1], v[220:221], v[40:41]
	v_pk_mul_f32 v[2:3], v[222:223], v[22:23]
	v_pk_mul_f32 v[4:5], v[224:225], v[20:21]
	v_pk_mul_f32 v[6:7], v[226:227], v[18:19]
	v_cvt_pk_bf16_f32 v0, v0, v1
	v_cvt_pk_bf16_f32 v1, v2, v3
	v_cvt_pk_bf16_f32 v2, v4, v5
	v_cvt_pk_bf16_f32 v3, v6, v7
	global_store_dwordx4 v[58:59], v[0:3], off offset:-1024
	s_nop 1
	s_nop 0
	v_pk_mul_f32 v[0:1], v[228:229], v[16:17]
	v_pk_mul_f32 v[2:3], v[230:231], v[10:11]
	v_pk_mul_f32 v[4:5], v[232:233], v[14:15]
	v_pk_mul_f32 v[6:7], v[234:235], v[8:9]
	v_cvt_pk_bf16_f32 v0, v0, v1
	v_cvt_pk_bf16_f32 v1, v2, v3
	v_cvt_pk_bf16_f32 v2, v4, v5
	v_cvt_pk_bf16_f32 v3, v6, v7
	global_store_dwordx4 v[58:59], v[0:3], off
	s_nop 1
	s_cbranch_scc1 .LBB0_743

; __device__ __forceinline__ unsigned pk2(float lo, float hi) { const f32x2 v = {lo, hi}; const hwbf16x2 r = __builtin_convertvector(v, hwbf16x2); return __builtin_bit_cast(unsigned, r); }
; __device__ __forceinline__ float bf_lo(unsigned v) { return __uint_as_float(v << 16); }
; __device__ __forceinline__ float bf_hi(unsigned v) { return __uint_as_float(v & 0xffff0000u); }
; __device__ __forceinline__ float silu_f(float x) { return x * __builtin_amdgcn_rcpf(1.0f + __expf(-x)); }
; __global__ void __launch_bounds__(NTHR) fwd(Args args) {
;     ...
;             for (int r = 0; r < 32; ++r) {
;                 const int m = m0 + r; v4u ng_ = zero, nu_ = zero;
;                 if ((m & (SEQ - 1)) != SEQ - 1) { ng_ = *(const v4u*)(GU + (size_t)(m + 1) * FF2 + c); nu_ = *(const v4u*)(GU + (size_t)(m + 1) * FF2 + FF + c); }
;                 v4u ov;
; #pragma unroll
;                 for (int e = 0; e < 4; ++e) {
;                     const float g0 = wg[0][2 * e] * bf_lo(pg_[e]) + wg[1][2 * e] * bf_lo(cg_[e]) + wg[2][2 * e] * bf_lo(ng_[e]);
;                     const float g1 = wg[0][2 * e + 1] * bf_hi(pg_[e]) + wg[1][2 * e + 1] * bf_hi(cg_[e]) + wg[2][2 * e + 1] * bf_hi(ng_[e]);
;                     const float u0 = wu[0][2 * e] * bf_lo(pu_[e]) + wu[1][2 * e] * bf_lo(cu_[e]) + wu[2][2 * e] * bf_lo(nu_[e]);
;                     const float u1 = wu[0][2 * e + 1] * bf_hi(pu_[e]) + wu[1][2 * e + 1] * bf_hi(cu_[e]) + wu[2][2 * e + 1] * bf_hi(nu_[e]);
;                     ov[e] = pk2(silu_f(g0) * u0, silu_f(g1) * u1);
;                 }
;                 *(v4u*)(ACT + (size_t)m * FF + c) = ov;
;                 pg_ = cg_; pu_ = cu_; cg_ = ng_; cu_ = nu_;
;             }
.LBB0_891:
	s_or_b64 exec, exec, s[40:41]
	v_mov_b64_e32 v[2:3], s[2:3]
	v_mad_i64_i32 v[2:3], s[40:41], v68, s42, v[2:3]
	v_lshlrev_b64 v[70:71], 1, v[76:77]
	v_lshl_add_u64 v[2:3], v[2:3], 0, v[70:71]
	v_add_co_u32_e32 v56, vcc, 0x5000, v2
	v_lshlrev_b32_e32 v1, 5, v69
	s_nop 0
	v_addc_co_u32_e32 v57, vcc, 0, v3, vcc
	global_load_dwordx4 v[52:55], v[2:3], off
	s_nop 0
	global_load_dwordx4 v[56:59], v[56:57], off offset:1536
	v_mad_i64_i32 v[2:3], s[40:41], v68, s43, v[70:71]
	s_mov_b32 s44, 0
	v_lshl_add_u64 v[78:79], s[0:1], 0, v[2:3]
	v_add_u32_e32 v80, 1, v68
	v_xor_b32_e32 v81, 0xfff, v1
	v_mov_b32_e32 v2, v0
	v_mov_b32_e32 v3, v0
	v_mov_b32_e32 v1, v0
	v_mov_b64_e32 v[70:71], v[2:3]
	v_mov_b64_e32 v[74:75], v[2:3]
	v_cmp_ne_u32_e32 vcc, s44, v81
	v_mov_b64_e32 v[68:69], v[0:1]
	v_mov_b64_e32 v[72:73], v[0:1]
	s_and_saveexec_b64 s[40:41], vcc
	v_add_u32_e32 v1, s44, v80
	v_mov_b64_e32 v[2:3], s[2:3]
	v_mad_i64_i32 v[2:3], s[46:47], v1, s42, v[2:3]
	v_lshl_add_u64 v[2:3], v[76:77], 1, v[2:3]
	v_add_co_u32_e32 v72, vcc, 0x5000, v2
	s_nop 1
	v_addc_co_u32_e32 v73, vcc, 0, v3, vcc
	global_load_dwordx4 v[68:71], v[2:3], off
	s_nop 0
	global_load_dwordx4 v[72:75], v[72:73], off offset:1536
	s_or_b64 exec, exec, s[40:41]
.Lp8_rows:
	v_mov_b32_e32 v2, v0
	v_mov_b32_e32 v3, v0
	v_mov_b32_e32 v1, v0
	v_mov_b64_e32 v[90:91], v[2:3]
	v_mov_b64_e32 v[94:95], v[2:3]
	s_add_i32 s46, s44, 1
	v_cmp_ne_u32_e32 vcc, s46, v81
	v_mov_b64_e32 v[88:89], v[0:1]
	v_mov_b64_e32 v[92:93], v[0:1]
	s_and_saveexec_b64 s[40:41], vcc
	v_add_u32_e32 v1, s46, v80
	v_mov_b64_e32 v[2:3], s[2:3]
	v_mad_i64_i32 v[2:3], s[46:47], v1, s42, v[2:3]
	v_lshl_add_u64 v[2:3], v[76:77], 1, v[2:3]
	v_add_co_u32_e32 v92, vcc, 0x5000, v2
	s_nop 1
	v_addc_co_u32_e32 v93, vcc, 0, v3, vcc
	global_load_dwordx4 v[88:91], v[2:3], off
	s_nop 0
	global_load_dwordx4 v[92:95], v[92:93], off offset:1536
	s_or_b64 exec, exec, s[40:41]
	s_waitcnt vmcnt(4)
	v_lshlrev_b32_e32 v82, 16, v52
	v_and_b32_e32 v83, 0xffff0000, v52
	v_lshlrev_b32_e32 v2, 16, v64
	v_and_b32_e32 v3, 0xffff0000, v64
	v_pk_mul_f32 v[82:83], v[24:25], v[82:83]
	s_waitcnt vmcnt(2)
	v_lshlrev_b32_e32 v84, 16, v56
	v_pk_fma_f32 v[2:3], v[8:9], v[2:3], v[82:83]
	v_lshlrev_b32_e32 v82, 16, v68
	v_and_b32_e32 v83, 0xffff0000, v68
	v_pk_fma_f32 v[2:3], v[40:41], v[82:83], v[2:3]
	v_lshlrev_b32_e32 v82, 16, v60
	v_mul_f32_e32 v1, 0xbfb8aa3b, v2
	v_and_b32_e32 v83, 0xffff0000, v60
	v_exp_f32_e32 v1, v1
	v_mul_f32_e32 v60, 0xbfb8aa3b, v3
	v_exp_f32_e32 v60, v60
	v_and_b32_e32 v85, 0xffff0000, v56
	v_pk_mul_f32 v[84:85], v[32:33], v[84:85]
	v_add_f32_e32 v1, 1.0, v1
	v_pk_fma_f32 v[82:83], v[16:17], v[82:83], v[84:85]
	v_rcp_f32_e32 v84, v1
	v_add_f32_e32 v1, 1.0, v60
	v_rcp_f32_e32 v85, v1
	v_lshlrev_b32_e32 v86, 16, v72
	v_and_b32_e32 v87, 0xffff0000, v72
	v_pk_fma_f32 v[82:83], v[48:49], v[86:87], v[82:83]
	v_pk_mul_f32 v[2:3], v[2:3], v[84:85]
	v_lshlrev_b32_e32 v64, 16, v53
	v_pk_mul_f32 v[2:3], v[2:3], v[82:83]
	v_lshlrev_b32_e32 v82, 16, v57
	v_cvt_pk_bf16_f32 v60, v2, v3
	v_lshlrev_b32_e32 v2, 16, v65
	v_and_b32_e32 v3, 0xffff0000, v65
	v_and_b32_e32 v65, 0xffff0000, v53
	v_pk_mul_f32 v[64:65], v[26:27], v[64:65]
	v_and_b32_e32 v83, 0xffff0000, v57
	v_pk_fma_f32 v[2:3], v[10:11], v[2:3], v[64:65]
	v_lshlrev_b32_e32 v64, 16, v69
	v_and_b32_e32 v65, 0xffff0000, v69
	v_pk_fma_f32 v[2:3], v[42:43], v[64:65], v[2:3]
	v_lshlrev_b32_e32 v64, 16, v61
	v_mul_f32_e32 v1, 0xbfb8aa3b, v2
	v_and_b32_e32 v65, 0xffff0000, v61
	v_exp_f32_e32 v1, v1
	v_mul_f32_e32 v61, 0xbfb8aa3b, v3
	v_exp_f32_e32 v61, v61
	v_pk_mul_f32 v[82:83], v[34:35], v[82:83]
	v_add_f32_e32 v1, 1.0, v1
	v_pk_fma_f32 v[64:65], v[18:19], v[64:65], v[82:83]
	v_rcp_f32_e32 v82, v1
	v_add_f32_e32 v1, 1.0, v61
	v_rcp_f32_e32 v83, v1
	v_lshlrev_b32_e32 v84, 16, v73
	v_and_b32_e32 v85, 0xffff0000, v73
	v_pk_fma_f32 v[64:65], v[50:51], v[84:85], v[64:65]
	v_pk_mul_f32 v[2:3], v[2:3], v[82:83]
	v_lshlrev_b32_e32 v82, 16, v58
	v_pk_mul_f32 v[2:3], v[2:3], v[64:65]
	v_lshlrev_b32_e32 v64, 16, v54
	v_and_b32_e32 v65, 0xffff0000, v54
	v_cvt_pk_bf16_f32 v61, v2, v3
	v_lshlrev_b32_e32 v2, 16, v66
	v_and_b32_e32 v3, 0xffff0000, v66
	v_pk_mul_f32 v[64:65], v[20:21], v[64:65]
	v_and_b32_e32 v83, 0xffff0000, v58
	v_pk_fma_f32 v[2:3], v[4:5], v[2:3], v[64:65]
	v_lshlrev_b32_e32 v64, 16, v70
	v_and_b32_e32 v65, 0xffff0000, v70
	v_pk_fma_f32 v[2:3], v[36:37], v[64:65], v[2:3]
	v_lshlrev_b32_e32 v64, 16, v62
	v_mul_f32_e32 v1, 0xbfb8aa3b, v2
	v_and_b32_e32 v65, 0xffff0000, v62
	v_exp_f32_e32 v1, v1
	v_mul_f32_e32 v62, 0xbfb8aa3b, v3
	v_exp_f32_e32 v62, v62
	v_pk_mul_f32 v[82:83], v[28:29], v[82:83]
	v_add_f32_e32 v1, 1.0, v1
	v_pk_fma_f32 v[64:65], v[12:13], v[64:65], v[82:83]
	v_rcp_f32_e32 v82, v1
	v_add_f32_e32 v1, 1.0, v62
	v_rcp_f32_e32 v83, v1
	v_lshlrev_b32_e32 v84, 16, v74
	v_and_b32_e32 v85, 0xffff0000, v74
	v_pk_fma_f32 v[64:65], v[44:45], v[84:85], v[64:65]
	v_pk_mul_f32 v[2:3], v[2:3], v[82:83]
	v_lshlrev_b32_e32 v66, 16, v59
	v_pk_mul_f32 v[2:3], v[2:3], v[64:65]
	v_lshlrev_b32_e32 v64, 16, v55
	v_and_b32_e32 v65, 0xffff0000, v55
	v_cvt_pk_bf16_f32 v62, v2, v3
	v_lshlrev_b32_e32 v2, 16, v67
	v_and_b32_e32 v3, 0xffff0000, v67
	v_pk_mul_f32 v[64:65], v[22:23], v[64:65]
	v_and_b32_e32 v67, 0xffff0000, v59
	v_pk_fma_f32 v[2:3], v[6:7], v[2:3], v[64:65]
	v_lshlrev_b32_e32 v64, 16, v71
	v_and_b32_e32 v65, 0xffff0000, v71
	v_pk_fma_f32 v[2:3], v[38:39], v[64:65], v[2:3]
	v_lshlrev_b32_e32 v64, 16, v63
	v_mul_f32_e32 v1, 0xbfb8aa3b, v2
	v_and_b32_e32 v65, 0xffff0000, v63
	v_exp_f32_e32 v1, v1
	v_mul_f32_e32 v63, 0xbfb8aa3b, v3
	v_exp_f32_e32 v63, v63
	v_pk_mul_f32 v[66:67], v[30:31], v[66:67]
; __device__ __forceinline__ unsigned pk2(float lo, float hi) { const f32x2 v = {lo, hi}; const hwbf16x2 r = __builtin_convertvector(v, hwbf16x2); return __builtin_bit_cast(unsigned, r); }
; __device__ __forceinline__ float bf_lo(unsigned v) { return __uint_as_float(v << 16); }
; __device__ __forceinline__ float bf_hi(unsigned v) { return __uint_as_float(v & 0xffff0000u); }
; __device__ __forceinline__ float silu_f(float x) { return x * __builtin_amdgcn_rcpf(1.0f + __expf(-x)); }
; __global__ void __launch_bounds__(NTHR) fwd(Args args) {
;     ...
;             for (int r = 0; r < 32; ++r) {
;                 const int m = m0 + r; v4u ng_ = zero, nu_ = zero;
;                 if ((m & (SEQ - 1)) != SEQ - 1) { ng_ = *(const v4u*)(GU + (size_t)(m + 1) * FF2 + c); nu_ = *(const v4u*)(GU + (size_t)(m + 1) * FF2 + FF + c); }
;                 v4u ov;
; #pragma unroll
;                 for (int e = 0; e < 4; ++e) {
;                     const float g0 = wg[0][2 * e] * bf_lo(pg_[e]) + wg[1][2 * e] * bf_lo(cg_[e]) + wg[2][2 * e] * bf_lo(ng_[e]);
;                     const float g1 = wg[0][2 * e + 1] * bf_hi(pg_[e]) + wg[1][2 * e + 1] * bf_hi(cg_[e]) + wg[2][2 * e + 1] * bf_hi(ng_[e]);
;                     const float u0 = wu[0][2 * e] * bf_lo(pu_[e]) + wu[1][2 * e] * bf_lo(cu_[e]) + wu[2][2 * e] * bf_lo(nu_[e]);
;                     const float u1 = wu[0][2 * e + 1] * bf_hi(pu_[e]) + wu[1][2 * e + 1] * bf_hi(cu_[e]) + wu[2][2 * e + 1] * bf_hi(nu_[e]);
;                     ov[e] = pk2(silu_f(g0) * u0, silu_f(g1) * u1);
;                 }
;                 *(v4u*)(ACT + (size_t)m * FF + c) = ov;
;                 pg_ = cg_; pu_ = cu_; cg_ = ng_; cu_ = nu_;
;             }
	v_add_f32_e32 v1, 1.0, v1
	v_pk_fma_f32 v[64:65], v[14:15], v[64:65], v[66:67]
	v_rcp_f32_e32 v66, v1
	v_add_f32_e32 v1, 1.0, v63
	v_rcp_f32_e32 v67, v1
	v_lshlrev_b32_e32 v82, 16, v75
	v_and_b32_e32 v83, 0xffff0000, v75
	v_pk_fma_f32 v[64:65], v[46:47], v[82:83], v[64:65]
	v_pk_mul_f32 v[2:3], v[2:3], v[66:67]
	s_add_i32 s44, s44, 1
	v_pk_mul_f32 v[2:3], v[2:3], v[64:65]
	v_mov_b64_e32 v[66:67], v[54:55]
	v_cvt_pk_bf16_f32 v63, v2, v3
	global_store_dwordx4 v[78:79], v[60:63], off
	v_mov_b64_e32 v[64:65], v[52:53]
	v_mov_b64_e32 v[52:53], v[68:69]
	v_mov_b64_e32 v[62:63], v[58:59]
	v_mov_b64_e32 v[60:61], v[56:57]
	v_mov_b64_e32 v[56:57], v[72:73]
	v_lshl_add_u64 v[78:79], v[78:79], 0, s[36:37]
	v_mov_b64_e32 v[54:55], v[70:71]
	v_mov_b64_e32 v[58:59], v[74:75]
	v_mov_b32_e32 v2, v0
	v_mov_b32_e32 v3, v0
	v_mov_b32_e32 v1, v0
	v_mov_b64_e32 v[70:71], v[2:3]
	v_mov_b64_e32 v[74:75], v[2:3]
	s_add_i32 s46, s44, 1
	v_cmp_ne_u32_e32 vcc, s46, v81
	v_mov_b64_e32 v[68:69], v[0:1]
	v_mov_b64_e32 v[72:73], v[0:1]
	s_and_saveexec_b64 s[40:41], vcc
	v_add_u32_e32 v1, s46, v80
	v_mov_b64_e32 v[2:3], s[2:3]
	v_mad_i64_i32 v[2:3], s[46:47], v1, s42, v[2:3]
	v_lshl_add_u64 v[2:3], v[76:77], 1, v[2:3]
	v_add_co_u32_e32 v72, vcc, 0x5000, v2
	s_nop 1
	v_addc_co_u32_e32 v73, vcc, 0, v3, vcc
	global_load_dwordx4 v[68:71], v[2:3], off
	s_nop 0
	global_load_dwordx4 v[72:75], v[72:73], off offset:1536
	s_or_b64 exec, exec, s[40:41]
	s_waitcnt vmcnt(4)
	v_lshlrev_b32_e32 v82, 16, v52
	v_and_b32_e32 v83, 0xffff0000, v52
	v_lshlrev_b32_e32 v2, 16, v64
	v_and_b32_e32 v3, 0xffff0000, v64
	v_pk_mul_f32 v[82:83], v[24:25], v[82:83]
	s_waitcnt vmcnt(2)
	v_lshlrev_b32_e32 v84, 16, v56
	v_pk_fma_f32 v[2:3], v[8:9], v[2:3], v[82:83]
	v_lshlrev_b32_e32 v82, 16, v88
	v_and_b32_e32 v83, 0xffff0000, v88
	v_pk_fma_f32 v[2:3], v[40:41], v[82:83], v[2:3]
	v_lshlrev_b32_e32 v82, 16, v60
	v_mul_f32_e32 v1, 0xbfb8aa3b, v2
	v_and_b32_e32 v83, 0xffff0000, v60
	v_exp_f32_e32 v1, v1
	v_mul_f32_e32 v60, 0xbfb8aa3b, v3
	v_exp_f32_e32 v60, v60
	v_and_b32_e32 v85, 0xffff0000, v56
	v_pk_mul_f32 v[84:85], v[32:33], v[84:85]
	v_add_f32_e32 v1, 1.0, v1
	v_pk_fma_f32 v[82:83], v[16:17], v[82:83], v[84:85]
	v_rcp_f32_e32 v84, v1
	v_add_f32_e32 v1, 1.0, v60
	v_rcp_f32_e32 v85, v1
	v_lshlrev_b32_e32 v86, 16, v92
	v_and_b32_e32 v87, 0xffff0000, v92
	v_pk_fma_f32 v[82:83], v[48:49], v[86:87], v[82:83]
	v_pk_mul_f32 v[2:3], v[2:3], v[84:85]
	v_lshlrev_b32_e32 v64, 16, v53
	v_pk_mul_f32 v[2:3], v[2:3], v[82:83]
	v_lshlrev_b32_e32 v82, 16, v57
	v_cvt_pk_bf16_f32 v60, v2, v3
	v_lshlrev_b32_e32 v2, 16, v65
	v_and_b32_e32 v3, 0xffff0000, v65
	v_and_b32_e32 v65, 0xffff0000, v53
	v_pk_mul_f32 v[64:65], v[26:27], v[64:65]
	v_and_b32_e32 v83, 0xffff0000, v57
	v_pk_fma_f32 v[2:3], v[10:11], v[2:3], v[64:65]
	v_lshlrev_b32_e32 v64, 16, v89
	v_and_b32_e32 v65, 0xffff0000, v89
	v_pk_fma_f32 v[2:3], v[42:43], v[64:65], v[2:3]
	v_lshlrev_b32_e32 v64, 16, v61
	v_mul_f32_e32 v1, 0xbfb8aa3b, v2
	v_and_b32_e32 v65, 0xffff0000, v61
	v_exp_f32_e32 v1, v1
	v_mul_f32_e32 v61, 0xbfb8aa3b, v3
	v_exp_f32_e32 v61, v61
	v_pk_mul_f32 v[82:83], v[34:35], v[82:83]
	v_add_f32_e32 v1, 1.0, v1
	v_pk_fma_f32 v[64:65], v[18:19], v[64:65], v[82:83]
	v_rcp_f32_e32 v82, v1
	v_add_f32_e32 v1, 1.0, v61
	v_rcp_f32_e32 v83, v1
	v_lshlrev_b32_e32 v84, 16, v93
	v_and_b32_e32 v85, 0xffff0000, v93
	v_pk_fma_f32 v[64:65], v[50:51], v[84:85], v[64:65]
	v_pk_mul_f32 v[2:3], v[2:3], v[82:83]
	v_lshlrev_b32_e32 v82, 16, v58
	v_pk_mul_f32 v[2:3], v[2:3], v[64:65]
	v_lshlrev_b32_e32 v64, 16, v54
	v_and_b32_e32 v65, 0xffff0000, v54
	v_cvt_pk_bf16_f32 v61, v2, v3
	v_lshlrev_b32_e32 v2, 16, v66
	v_and_b32_e32 v3, 0xffff0000, v66
	v_pk_mul_f32 v[64:65], v[20:21], v[64:65]
	v_and_b32_e32 v83, 0xffff0000, v58
	v_pk_fma_f32 v[2:3], v[4:5], v[2:3], v[64:65]
	v_lshlrev_b32_e32 v64, 16, v90
	v_and_b32_e32 v65, 0xffff0000, v90
	v_pk_fma_f32 v[2:3], v[36:37], v[64:65], v[2:3]
	v_lshlrev_b32_e32 v64, 16, v62
	v_mul_f32_e32 v1, 0xbfb8aa3b, v2
	v_and_b32_e32 v65, 0xffff0000, v62
	v_exp_f32_e32 v1, v1
	v_mul_f32_e32 v62, 0xbfb8aa3b, v3
	v_exp_f32_e32 v62, v62
	v_pk_mul_f32 v[82:83], v[28:29], v[82:83]
	v_add_f32_e32 v1, 1.0, v1
	v_pk_fma_f32 v[64:65], v[12:13], v[64:65], v[82:83]
	v_rcp_f32_e32 v82, v1
	v_add_f32_e32 v1, 1.0, v62
	v_rcp_f32_e32 v83, v1
	v_lshlrev_b32_e32 v84, 16, v94
	v_and_b32_e32 v85, 0xffff0000, v94
	v_pk_fma_f32 v[64:65], v[44:45], v[84:85], v[64:65]
	v_pk_mul_f32 v[2:3], v[2:3], v[82:83]
	v_lshlrev_b32_e32 v66, 16, v59
	v_pk_mul_f32 v[2:3], v[2:3], v[64:65]
	v_lshlrev_b32_e32 v64, 16, v55
	v_and_b32_e32 v65, 0xffff0000, v55
	v_cvt_pk_bf16_f32 v62, v2, v3
	v_lshlrev_b32_e32 v2, 16, v67
	v_and_b32_e32 v3, 0xffff0000, v67
	v_pk_mul_f32 v[64:65], v[22:23], v[64:65]
	v_and_b32_e32 v67, 0xffff0000, v59
	v_pk_fma_f32 v[2:3], v[6:7], v[2:3], v[64:65]
	v_lshlrev_b32_e32 v64, 16, v91
	v_and_b32_e32 v65, 0xffff0000, v91
	v_pk_fma_f32 v[2:3], v[38:39], v[64:65], v[2:3]
	v_lshlrev_b32_e32 v64, 16, v63
	v_mul_f32_e32 v1, 0xbfb8aa3b, v2
	v_and_b32_e32 v65, 0xffff0000, v63
	v_exp_f32_e32 v1, v1
	v_mul_f32_e32 v63, 0xbfb8aa3b, v3
	v_exp_f32_e32 v63, v63
	v_pk_mul_f32 v[66:67], v[30:31], v[66:67]
	v_add_f32_e32 v1, 1.0, v1
	v_pk_fma_f32 v[64:65], v[14:15], v[64:65], v[66:67]
	v_rcp_f32_e32 v66, v1
	v_add_f32_e32 v1, 1.0, v63
	v_rcp_f32_e32 v67, v1
	v_lshlrev_b32_e32 v82, 16, v95
	v_and_b32_e32 v83, 0xffff0000, v95
	v_pk_fma_f32 v[64:65], v[46:47], v[82:83], v[64:65]
	v_pk_mul_f32 v[2:3], v[2:3], v[66:67]
	s_add_i32 s44, s44, 1
	v_pk_mul_f32 v[2:3], v[2:3], v[64:65]
	v_mov_b64_e32 v[66:67], v[54:55]
	v_cvt_pk_bf16_f32 v63, v2, v3
	global_store_dwordx4 v[78:79], v[60:63], off
	v_mov_b64_e32 v[64:65], v[52:53]
	v_mov_b64_e32 v[52:53], v[88:89]
	v_mov_b64_e32 v[62:63], v[58:59]
	v_mov_b64_e32 v[60:61], v[56:57]
	v_mov_b64_e32 v[56:57], v[92:93]
	v_lshl_add_u64 v[78:79], v[78:79], 0, s[36:37]
	v_mov_b64_e32 v[54:55], v[90:91]
	v_mov_b64_e32 v[58:59], v[94:95]
	s_cmp_eq_u32 s44, 32
	s_cbranch_scc0 .Lp8_rows
	s_waitcnt vmcnt(0)
	s_branch .LBB0_888

; __device__ __forceinline__ unsigned pk2(float lo, float hi) { const f32x2 v = {lo, hi}; const hwbf16x2 r = __builtin_convertvector(v, hwbf16x2); return __builtin_bit_cast(unsigned, r); }
; __device__ __forceinline__ float bf_lo(unsigned v) { return __uint_as_float(v << 16); }
; __device__ __forceinline__ float bf_hi(unsigned v) { return __uint_as_float(v & 0xffff0000u); }
; __device__ __forceinline__ void rms_rowb_to_bf16(const bf16* hrow, const float* w, bf16* orow, int lane) {
;     const v4u* hr = (const v4u*)hrow + lane; float v[8][8]; float s = 0.f;
; #pragma unroll
;     for (int j = 0; j < 8; ++j) { const v4u q = hr[64 * j];
;         v[j][0] = bf_lo(q.x); v[j][1] = bf_hi(q.x); v[j][2] = bf_lo(q.y); v[j][3] = bf_hi(q.y); v[j][4] = bf_lo(q.z); v[j][5] = bf_hi(q.z); v[j][6] = bf_lo(q.w); v[j][7] = bf_hi(q.w);
; #pragma unroll
;         for (int e = 0; e < 8; ++e) s += v[j][e] * v[j][e]; }
;     const float r = rsqrtf(wave_sum(s) * (1.f / D) + EPS);
;     v4u* o = (v4u*)orow + lane;
; #pragma unroll
;     for (int j = 0; j < 8; ++j) { const f32x4 g0 = *(const f32x4*)(w + (64 * j + lane) * 8), g1 = *(const f32x4*)(w + (64 * j + lane) * 8 + 4);
;         v4u q; q.x = pk2(v[j][0] * r * g0.x, v[j][1] * r * g0.y); q.y = pk2(v[j][2] * r * g0.z, v[j][3] * r * g0.w); q.z = pk2(v[j][4] * r * g1.x, v[j][5] * r * g1.y); q.w = pk2(v[j][6] * r * g1.z, v[j][7] * r * g1.w);
;         o[64 * j] = q; }
.LBB0_1033:
	s_cmp_lt_i32 s30, 11
	s_cselect_b64 s[4:5], -1, 0
	s_and_b64 s[0:1], s[4:5], s[0:1]
	s_and_b64 s[0:1], s[0:1], s[10:11]
	s_andn2_b64 vcc, exec, s[0:1]
	s_cbranch_vccnz .LBB0_1036
	s_waitcnt vmcnt(0)
	v_mbcnt_hi_u32_b32 v0, -1, v168
	v_and_b32_e32 v1, 64, v0
	v_add_u32_e32 v1, 64, v1
	v_xor_b32_e32 v2, 1, v0
	v_cmp_lt_i32_e32 vcc, v2, v1
	v_readlane_b32 s36, v253, 6
	v_mov_b32_e32 v145, 0
	v_cndmask_b32_e32 v2, v0, v2, vcc
	v_lshlrev_b32_e32 v60, 2, v2
	v_xor_b32_e32 v2, 2, v0
	v_cmp_lt_i32_e32 vcc, v2, v1
	v_readlane_b32 s46, v253, 16
	v_readlane_b32 s47, v253, 17
	v_cndmask_b32_e32 v2, v0, v2, vcc
	v_lshlrev_b32_e32 v61, 2, v2
	v_xor_b32_e32 v2, 4, v0
	v_cmp_lt_i32_e32 vcc, v2, v1
	v_lshl_add_u64 v[24:25], s[46:47], 0, v[144:145]
	s_mov_b64 s[0:1], 0x1000
	v_cndmask_b32_e32 v2, v0, v2, vcc
	v_lshlrev_b32_e32 v62, 2, v2
	v_xor_b32_e32 v2, 8, v0
	v_cmp_lt_i32_e32 vcc, v2, v1
	v_lshl_add_u64 v[26:27], v[24:25], 0, s[0:1]
	s_mov_b64 s[0:1], 0x1800
	v_cndmask_b32_e32 v2, v0, v2, vcc
	v_lshl_add_u64 v[28:29], v[24:25], 0, s[0:1]
	s_mov_b64 s[0:1], 0x2000
	v_lshlrev_b32_e32 v63, 2, v2
	v_xor_b32_e32 v2, 16, v0
	v_lshl_add_u64 v[30:31], v[24:25], 0, s[0:1]
	s_mov_b64 s[0:1], 0x2800
	v_cmp_lt_i32_e32 vcc, v2, v1
	v_lshl_add_u64 v[32:33], v[24:25], 0, s[0:1]
	s_mov_b64 s[0:1], 0x3000
	v_cndmask_b32_e32 v2, v0, v2, vcc
	v_lshl_add_u64 v[34:35], v[24:25], 0, s[0:1]
	s_mov_b64 s[0:1], 0x3800
	s_ashr_i32 s93, s92, 31
	v_lshlrev_b32_e32 v64, 2, v2
	v_xor_b32_e32 v2, 32, v0
	v_lshl_add_u64 v[36:37], v[24:25], 0, s[0:1]
	s_lshl_b64 s[0:1], s[92:93], 13
	v_cmp_lt_i32_e32 vcc, v2, v1
	s_add_u32 s0, s28, s0
	v_mov_b32_e32 v147, v145
	v_cndmask_b32_e32 v0, v0, v2, vcc
	s_addc_u32 s1, s29, s1
	v_lshlrev_b32_e32 v65, 2, v0
	v_lshl_add_u64 v[0:1], s[0:1], 0, v[146:147]
	s_mov_b64 s[0:1], 0x1c801c00
	s_ashr_i32 s95, s94, 31
	v_lshl_add_u64 v[38:39], v[0:1], 0, s[0:1]
	s_lshl_b64 s[6:7], s[94:95], 13
	v_mov_b32_e32 v66, 0x358637bd
	s_mov_b32 s12, 0x800000
	s_mov_b32 s13, 0xfbfff000
	s_brev_b32 s14, 63
	s_mov_b32 s15, s92
	v_readlane_b32 s37, v253, 7
	v_readlane_b32 s38, v253, 8
	v_readlane_b32 s39, v253, 9
	v_readlane_b32 s40, v253, 10
	v_readlane_b32 s41, v253, 11
	v_readlane_b32 s42, v253, 12
	v_readlane_b32 s43, v253, 13
	v_readlane_b32 s44, v253, 14
	v_readlane_b32 s45, v253, 15
	v_readlane_b32 s48, v253, 18
	v_readlane_b32 s49, v253, 19
	v_readlane_b32 s50, v253, 20
	v_readlane_b32 s51, v253, 21
	global_load_dwordx4 v[172:175], v[24:25], off offset:16
	global_load_dwordx4 v[176:179], v[24:25], off
	global_load_dwordx4 v[180:183], v[24:25], off offset:2048
	global_load_dwordx4 v[184:187], v[24:25], off offset:2064
	global_load_dwordx4 v[188:191], v[26:27], off
	global_load_dwordx4 v[192:195], v[26:27], off offset:16
	global_load_dwordx4 v[196:199], v[28:29], off
	global_load_dwordx4 v[200:203], v[28:29], off offset:16
	global_load_dwordx4 v[204:207], v[30:31], off
	global_load_dwordx4 v[208:211], v[30:31], off offset:16
	global_load_dwordx4 v[212:215], v[32:33], off
	global_load_dwordx4 v[216:219], v[32:33], off offset:16
	global_load_dwordx4 v[220:223], v[34:35], off
	global_load_dwordx4 v[224:227], v[34:35], off offset:16
	global_load_dwordx4 v[228:231], v[36:37], off
	global_load_dwordx4 v[232:235], v[36:37], off offset:16
.LBB0_1035:
	v_add_co_u32_e32 v40, vcc, 0xfffff000, v38
	global_load_dwordx4 v[20:23], v[38:39], off offset:-3072
	global_load_dwordx4 v[16:19], v[38:39], off offset:-2048
	global_load_dwordx4 v[12:15], v[38:39], off offset:-1024
	global_load_dwordx4 v[8:11], v[38:39], off
	v_addc_co_u32_e32 v41, vcc, -1, v39, vcc
	global_load_dwordx4 v[68:71], v[40:41], off offset:-3072
	global_load_dwordx4 v[72:75], v[40:41], off offset:-2048
	global_load_dwordx4 v[76:79], v[40:41], off offset:-1024
	global_load_dwordx4 v[80:83], v[38:39], off offset:-4096
	v_add_co_u32_e64 v58, s[0:1], s13, v38
	s_add_i32 s15, s15, s94
	s_nop 0
	v_addc_co_u32_e64 v59, s[0:1], -1, v39, s[0:1]
	s_cmpk_lt_i32 s15, 0x2000
	s_waitcnt vmcnt(7)
	v_lshlrev_b32_e32 v56, 16, v20
	v_and_b32_e32 v57, 0xffff0000, v20
	v_pk_mul_f32 v[88:89], v[56:57], v[56:57]
	v_lshlrev_b32_e32 v54, 16, v21
	s_waitcnt vmcnt(3)
	v_lshlrev_b32_e32 v118, 16, v68
	v_and_b32_e32 v119, 0xffff0000, v68
	v_lshlrev_b32_e32 v114, 16, v71
	v_and_b32_e32 v115, 0xffff0000, v71
	v_lshlrev_b32_e32 v116, 16, v70
	v_and_b32_e32 v117, 0xffff0000, v70
	v_lshlrev_b32_e32 v70, 16, v69
	v_and_b32_e32 v71, 0xffff0000, v69
	v_pk_mul_f32 v[136:137], v[118:119], v[118:119]
	v_pk_mul_f32 v[134:135], v[70:71], v[70:71]
	v_add_f32_e32 v67, v136, v137
	v_add_f32_e32 v67, v134, v67
	v_pk_mul_f32 v[132:133], v[116:117], v[116:117]
	v_add_f32_e32 v67, v135, v67
	v_add_f32_e32 v67, v132, v67
	s_waitcnt vmcnt(2)
	v_lshlrev_b32_e32 v68, 16, v75
	v_and_b32_e32 v69, 0xffff0000, v75
	v_lshlrev_b32_e32 v120, 16, v74
	v_and_b32_e32 v121, 0xffff0000, v74
	v_lshlrev_b32_e32 v74, 16, v73
	v_and_b32_e32 v75, 0xffff0000, v73
	v_lshlrev_b32_e32 v122, 16, v72
	v_and_b32_e32 v123, 0xffff0000, v72
	s_waitcnt vmcnt(1)
	v_lshlrev_b32_e32 v72, 16, v79
	v_and_b32_e32 v73, 0xffff0000, v79
	v_lshlrev_b32_e32 v124, 16, v78
	v_and_b32_e32 v125, 0xffff0000, v78
	v_lshlrev_b32_e32 v78, 16, v77
	v_and_b32_e32 v79, 0xffff0000, v77
	v_lshlrev_b32_e32 v126, 16, v76
	v_and_b32_e32 v127, 0xffff0000, v76
	s_waitcnt vmcnt(0)
; __device__ __forceinline__ float bf_lo(unsigned v) { return __uint_as_float(v << 16); }
; __device__ __forceinline__ float bf_hi(unsigned v) { return __uint_as_float(v & 0xffff0000u); }
; __device__ __forceinline__ void rms_rowb_to_bf16(const bf16* hrow, const float* w, bf16* orow, int lane) {
;     const v4u* hr = (const v4u*)hrow + lane; float v[8][8]; float s = 0.f;
; #pragma unroll
;     for (int j = 0; j < 8; ++j) { const v4u q = hr[64 * j];
;         v[j][0] = bf_lo(q.x); v[j][1] = bf_hi(q.x); v[j][2] = bf_lo(q.y); v[j][3] = bf_hi(q.y); v[j][4] = bf_lo(q.z); v[j][5] = bf_hi(q.z); v[j][6] = bf_lo(q.w); v[j][7] = bf_hi(q.w);
; #pragma unroll
;         for (int e = 0; e < 8; ++e) s += v[j][e] * v[j][e]; }
;     const float r = rsqrtf(wave_sum(s) * (1.f / D) + EPS);
	v_lshlrev_b32_e32 v76, 16, v83
	v_and_b32_e32 v77, 0xffff0000, v83
	v_lshlrev_b32_e32 v128, 16, v82
	v_and_b32_e32 v129, 0xffff0000, v82
	v_lshlrev_b32_e32 v82, 16, v81
	v_and_b32_e32 v83, 0xffff0000, v81
	v_lshlrev_b32_e32 v130, 16, v80
	v_and_b32_e32 v131, 0xffff0000, v80
	v_pk_mul_f32 v[80:81], v[114:115], v[114:115]
	v_add_f32_e32 v67, v133, v67
	v_add_f32_e32 v67, v80, v67
	v_pk_mul_f32 v[150:151], v[122:123], v[122:123]
	v_add_f32_e32 v67, v81, v67
	v_add_f32_e32 v67, v150, v67
	v_pk_mul_f32 v[148:149], v[74:75], v[74:75]
	v_add_f32_e32 v67, v151, v67
	v_add_f32_e32 v67, v148, v67
	v_pk_mul_f32 v[142:143], v[120:121], v[120:121]
	v_add_f32_e32 v67, v149, v67
	v_add_f32_e32 v67, v142, v67
	v_pk_mul_f32 v[138:139], v[68:69], v[68:69]
	v_add_f32_e32 v67, v143, v67
	v_add_f32_e32 v67, v138, v67
	v_pk_mul_f32 v[158:159], v[126:127], v[126:127]
	v_add_f32_e32 v67, v139, v67
	v_add_f32_e32 v67, v158, v67
	v_pk_mul_f32 v[156:157], v[78:79], v[78:79]
	v_add_f32_e32 v67, v159, v67
	v_add_f32_e32 v67, v156, v67
	v_pk_mul_f32 v[154:155], v[124:125], v[124:125]
	v_add_f32_e32 v67, v157, v67
	v_add_f32_e32 v67, v154, v67
	v_pk_mul_f32 v[152:153], v[72:73], v[72:73]
	v_add_f32_e32 v67, v155, v67
	v_add_f32_e32 v67, v152, v67
	v_pk_mul_f32 v[166:167], v[130:131], v[130:131]
	v_add_f32_e32 v67, v153, v67
	v_add_f32_e32 v67, v166, v67
	v_pk_mul_f32 v[164:165], v[82:83], v[82:83]
	v_add_f32_e32 v67, v167, v67
	v_add_f32_e32 v67, v164, v67
	v_pk_mul_f32 v[162:163], v[128:129], v[128:129]
	v_add_f32_e32 v67, v165, v67
	v_add_f32_e32 v67, v162, v67
	v_pk_mul_f32 v[160:161], v[76:77], v[76:77]
	v_add_f32_e32 v67, v163, v67
	v_add_f32_e32 v67, v160, v67
	v_add_f32_e32 v67, v161, v67
	v_and_b32_e32 v55, 0xffff0000, v21
	v_add_f32_e32 v67, v88, v67
	v_pk_mul_f32 v[86:87], v[54:55], v[54:55]
	v_add_f32_e32 v67, v89, v67
	v_lshlrev_b32_e32 v52, 16, v22
	v_and_b32_e32 v53, 0xffff0000, v22
	v_add_f32_e32 v67, v86, v67
	v_pk_mul_f32 v[84:85], v[52:53], v[52:53]
	v_add_f32_e32 v67, v87, v67
	v_lshlrev_b32_e32 v50, 16, v23
	v_and_b32_e32 v51, 0xffff0000, v23
	v_add_f32_e32 v67, v84, v67
	v_lshlrev_b32_e32 v42, 16, v19
	v_and_b32_e32 v43, 0xffff0000, v19
	v_lshlrev_b32_e32 v44, 16, v18
	v_and_b32_e32 v45, 0xffff0000, v18
	v_lshlrev_b32_e32 v46, 16, v17
	v_and_b32_e32 v47, 0xffff0000, v17
	v_lshlrev_b32_e32 v48, 16, v16
	v_and_b32_e32 v49, 0xffff0000, v16
	v_lshlrev_b32_e32 v18, 16, v15
	v_and_b32_e32 v19, 0xffff0000, v15
	v_lshlrev_b32_e32 v20, 16, v14
	v_and_b32_e32 v21, 0xffff0000, v14
	v_lshlrev_b32_e32 v22, 16, v13
	v_and_b32_e32 v23, 0xffff0000, v13
	v_lshlrev_b32_e32 v40, 16, v12
	v_and_b32_e32 v41, 0xffff0000, v12
	v_lshlrev_b32_e32 v12, 16, v11
	v_and_b32_e32 v13, 0xffff0000, v11
	v_lshlrev_b32_e32 v14, 16, v10
	v_and_b32_e32 v15, 0xffff0000, v10
	v_lshlrev_b32_e32 v10, 16, v9
	v_and_b32_e32 v11, 0xffff0000, v9
	v_lshlrev_b32_e32 v16, 16, v8
	v_and_b32_e32 v17, 0xffff0000, v8
	v_pk_mul_f32 v[8:9], v[50:51], v[50:51]
	v_add_f32_e32 v67, v85, v67
	v_add_f32_e32 v8, v8, v67
	v_pk_mul_f32 v[96:97], v[48:49], v[48:49]
	v_add_f32_e32 v8, v9, v8
	v_add_f32_e32 v8, v96, v8
	v_pk_mul_f32 v[94:95], v[46:47], v[46:47]
	v_add_f32_e32 v8, v97, v8
	v_add_f32_e32 v8, v94, v8
	v_pk_mul_f32 v[92:93], v[44:45], v[44:45]
	v_add_f32_e32 v8, v95, v8
	v_add_f32_e32 v8, v92, v8
	v_pk_mul_f32 v[90:91], v[42:43], v[42:43]
	v_add_f32_e32 v8, v93, v8
	v_add_f32_e32 v8, v90, v8
	v_pk_mul_f32 v[104:105], v[40:41], v[40:41]
	v_add_f32_e32 v8, v91, v8
	v_add_f32_e32 v8, v104, v8
	v_pk_mul_f32 v[102:103], v[22:23], v[22:23]
	v_add_f32_e32 v8, v105, v8
	v_add_f32_e32 v8, v102, v8
	v_pk_mul_f32 v[100:101], v[20:21], v[20:21]
	v_add_f32_e32 v8, v103, v8
	v_add_f32_e32 v8, v100, v8
	v_pk_mul_f32 v[98:99], v[18:19], v[18:19]
	v_add_f32_e32 v8, v101, v8
	v_add_f32_e32 v8, v98, v8
	v_pk_mul_f32 v[112:113], v[16:17], v[16:17]
	v_add_f32_e32 v8, v99, v8
	v_add_f32_e32 v8, v112, v8
	v_pk_mul_f32 v[110:111], v[10:11], v[10:11]
	v_add_f32_e32 v8, v113, v8
	v_add_f32_e32 v8, v110, v8
	v_pk_mul_f32 v[108:109], v[14:15], v[14:15]
	v_add_f32_e32 v8, v111, v8
	v_add_f32_e32 v8, v108, v8
	v_pk_mul_f32 v[106:107], v[12:13], v[12:13]
	v_add_f32_e32 v8, v109, v8
	v_add_f32_e32 v8, v106, v8
	v_add_f32_e32 v8, v107, v8
	ds_bpermute_b32 v9, v60, v8
	s_waitcnt lgkmcnt(0)
	v_add_f32_e32 v8, v8, v9
	ds_bpermute_b32 v9, v61, v8
	s_waitcnt lgkmcnt(0)
	v_add_f32_e32 v8, v8, v9
	ds_bpermute_b32 v9, v62, v8
	s_waitcnt lgkmcnt(0)
	v_add_f32_e32 v8, v8, v9
	ds_bpermute_b32 v9, v63, v8
	s_waitcnt lgkmcnt(0)
	v_add_f32_e32 v8, v8, v9
	ds_bpermute_b32 v9, v64, v8
	s_waitcnt lgkmcnt(0)
	v_add_f32_e32 v8, v8, v9
	ds_bpermute_b32 v9, v65, v8
	s_waitcnt lgkmcnt(0)
; __device__ __forceinline__ unsigned pk2(float lo, float hi) { const f32x2 v = {lo, hi}; const hwbf16x2 r = __builtin_convertvector(v, hwbf16x2); return __builtin_bit_cast(unsigned, r); }
; __device__ __forceinline__ void rms_rowb_to_bf16(const bf16* hrow, const float* w, bf16* orow, int lane) {
;     ...
;     const float r = rsqrtf(wave_sum(s) * (1.f / D) + EPS);
;     v4u* o = (v4u*)orow + lane;
; #pragma unroll
;     for (int j = 0; j < 8; ++j) { const f32x4 g0 = *(const f32x4*)(w + (64 * j + lane) * 8), g1 = *(const f32x4*)(w + (64 * j + lane) * 8 + 4);
;         v4u q; q.x = pk2(v[j][0] * r * g0.x, v[j][1] * r * g0.y); q.y = pk2(v[j][2] * r * g0.z, v[j][3] * r * g0.w); q.z = pk2(v[j][4] * r * g1.x, v[j][5] * r * g1.y); q.w = pk2(v[j][6] * r * g1.z, v[j][7] * r * g1.w);
;         o[64 * j] = q; }
	v_add_f32_e32 v8, v8, v9
	v_fmamk_f32 v8, v8, 0x39800000, v66
	v_mul_f32_e32 v9, 0x4b800000, v8
	v_cmp_gt_f32_e32 vcc, s12, v8
	s_nop 1
	v_cndmask_b32_e32 v8, v8, v9, vcc
	v_rsq_f32_e32 v8, v8
	s_nop 0
	v_mul_f32_e32 v9, 0x45800000, v8
	v_cndmask_b32_e32 v8, v8, v9, vcc
	v_pk_mul_f32 v[80:81], v[8:9], v[118:119] op_sel_hi:[0,1]
	v_pk_mul_f32 v[70:71], v[8:9], v[70:71] op_sel_hi:[0,1]
	v_pk_mul_f32 v[84:85], v[8:9], v[116:117] op_sel_hi:[0,1]
	v_pk_mul_f32 v[86:87], v[8:9], v[114:115] op_sel_hi:[0,1]
	v_pk_mul_f32 v[4:5], v[176:177], v[80:81]
	v_pk_mul_f32 v[6:7], v[178:179], v[70:71]
	v_pk_mul_f32 v[70:71], v[172:173], v[84:85]
	v_pk_mul_f32 v[80:81], v[174:175], v[86:87]
	v_cvt_pk_bf16_f32 v0, v4, v5
	v_cvt_pk_bf16_f32 v1, v6, v7
	v_cvt_pk_bf16_f32 v2, v70, v71
	v_cvt_pk_bf16_f32 v3, v80, v81
	global_store_dwordx4 v[58:59], v[0:3], off offset:-3072
	s_nop 1
	s_nop 0
	v_pk_mul_f32 v[70:71], v[8:9], v[122:123] op_sel_hi:[0,1]
	v_pk_mul_f32 v[74:75], v[8:9], v[74:75] op_sel_hi:[0,1]
	v_pk_mul_f32 v[80:81], v[8:9], v[120:121] op_sel_hi:[0,1]
	v_pk_mul_f32 v[68:69], v[8:9], v[68:69] op_sel_hi:[0,1]
	v_pk_mul_f32 v[72:73], v[8:9], v[72:73] op_sel_hi:[0,1]
	v_pk_mul_f32 v[56:57], v[8:9], v[56:57] op_sel_hi:[0,1]
	v_pk_mul_f32 v[54:55], v[8:9], v[54:55] op_sel_hi:[0,1]
	v_pk_mul_f32 v[52:53], v[8:9], v[52:53] op_sel_hi:[0,1]
	v_pk_mul_f32 v[50:51], v[8:9], v[50:51] op_sel_hi:[0,1]
	v_pk_mul_f32 v[48:49], v[8:9], v[48:49] op_sel_hi:[0,1]
	v_pk_mul_f32 v[46:47], v[8:9], v[46:47] op_sel_hi:[0,1]
	v_pk_mul_f32 v[44:45], v[8:9], v[44:45] op_sel_hi:[0,1]
	v_pk_mul_f32 v[42:43], v[8:9], v[42:43] op_sel_hi:[0,1]
	v_pk_mul_f32 v[40:41], v[8:9], v[40:41] op_sel_hi:[0,1]
	v_pk_mul_f32 v[22:23], v[8:9], v[22:23] op_sel_hi:[0,1]
	v_pk_mul_f32 v[20:21], v[8:9], v[20:21] op_sel_hi:[0,1]
	v_pk_mul_f32 v[18:19], v[8:9], v[18:19] op_sel_hi:[0,1]
	v_pk_mul_f32 v[16:17], v[8:9], v[16:17] op_sel_hi:[0,1]
	v_pk_mul_f32 v[10:11], v[8:9], v[10:11] op_sel_hi:[0,1]
	v_pk_mul_f32 v[14:15], v[8:9], v[14:15] op_sel_hi:[0,1]
	v_pk_mul_f32 v[0:1], v[180:181], v[70:71]
	v_pk_mul_f32 v[2:3], v[182:183], v[74:75]
	v_pk_mul_f32 v[4:5], v[184:185], v[80:81]
	v_pk_mul_f32 v[6:7], v[186:187], v[68:69]
	v_cvt_pk_bf16_f32 v0, v0, v1
	v_cvt_pk_bf16_f32 v1, v2, v3
	v_cvt_pk_bf16_f32 v2, v4, v5
	v_cvt_pk_bf16_f32 v3, v6, v7
	global_store_dwordx4 v[58:59], v[0:3], off offset:-2048
	s_nop 1
	s_nop 0
	v_pk_mul_f32 v[68:69], v[8:9], v[126:127] op_sel_hi:[0,1]
	v_pk_mul_f32 v[70:71], v[8:9], v[78:79] op_sel_hi:[0,1]
	v_pk_mul_f32 v[74:75], v[8:9], v[124:125] op_sel_hi:[0,1]
	v_pk_mul_f32 v[0:1], v[188:189], v[68:69]
	v_pk_mul_f32 v[2:3], v[190:191], v[70:71]
	v_pk_mul_f32 v[4:5], v[192:193], v[74:75]
	v_pk_mul_f32 v[6:7], v[194:195], v[72:73]
	v_cvt_pk_bf16_f32 v0, v0, v1
	v_cvt_pk_bf16_f32 v1, v2, v3
	v_cvt_pk_bf16_f32 v2, v4, v5
	v_cvt_pk_bf16_f32 v3, v6, v7
	global_store_dwordx4 v[58:59], v[0:3], off offset:-1024
	s_nop 1
	s_nop 0
	v_pk_mul_f32 v[68:69], v[8:9], v[130:131] op_sel_hi:[0,1]
	v_pk_mul_f32 v[70:71], v[8:9], v[82:83] op_sel_hi:[0,1]
	v_pk_mul_f32 v[72:73], v[8:9], v[128:129] op_sel_hi:[0,1]
	v_pk_mul_f32 v[74:75], v[8:9], v[76:77] op_sel_hi:[0,1]
	v_add_co_u32_e32 v58, vcc, s14, v38
	v_pk_mul_f32 v[8:9], v[8:9], v[12:13] op_sel_hi:[0,1]
	s_nop 0
	v_addc_co_u32_e32 v59, vcc, -1, v39, vcc
	v_lshl_add_u64 v[38:39], v[38:39], 0, s[6:7]
	v_pk_mul_f32 v[0:1], v[196:197], v[68:69]
	v_pk_mul_f32 v[2:3], v[198:199], v[70:71]
	v_pk_mul_f32 v[4:5], v[200:201], v[72:73]
	v_pk_mul_f32 v[6:7], v[202:203], v[74:75]
	v_cvt_pk_bf16_f32 v0, v0, v1
	v_cvt_pk_bf16_f32 v1, v2, v3
	v_cvt_pk_bf16_f32 v2, v4, v5
	v_cvt_pk_bf16_f32 v3, v6, v7
	global_store_dwordx4 v[58:59], v[0:3], off offset:-4096
	s_nop 1
	s_nop 0
	v_pk_mul_f32 v[0:1], v[204:205], v[56:57]
	v_pk_mul_f32 v[2:3], v[206:207], v[54:55]
	v_pk_mul_f32 v[4:5], v[208:209], v[52:53]
	v_pk_mul_f32 v[6:7], v[210:211], v[50:51]
	v_cvt_pk_bf16_f32 v0, v0, v1
	v_cvt_pk_bf16_f32 v1, v2, v3
	v_cvt_pk_bf16_f32 v2, v4, v5
	v_cvt_pk_bf16_f32 v3, v6, v7
	global_store_dwordx4 v[58:59], v[0:3], off offset:-3072
	s_nop 1
	s_nop 0
	v_pk_mul_f32 v[0:1], v[212:213], v[48:49]
	v_pk_mul_f32 v[2:3], v[214:215], v[46:47]
	v_pk_mul_f32 v[4:5], v[216:217], v[44:45]
	v_pk_mul_f32 v[6:7], v[218:219], v[42:43]
	v_cvt_pk_bf16_f32 v0, v0, v1
	v_cvt_pk_bf16_f32 v1, v2, v3
	v_cvt_pk_bf16_f32 v2, v4, v5
	v_cvt_pk_bf16_f32 v3, v6, v7
	global_store_dwordx4 v[58:59], v[0:3], off offset:-2048
	s_nop 1
	s_nop 0
	v_pk_mul_f32 v[0:1], v[220:221], v[40:41]
	v_pk_mul_f32 v[2:3], v[222:223], v[22:23]
	v_pk_mul_f32 v[4:5], v[224:225], v[20:21]
	v_pk_mul_f32 v[6:7], v[226:227], v[18:19]
	v_cvt_pk_bf16_f32 v0, v0, v1
	v_cvt_pk_bf16_f32 v1, v2, v3
	v_cvt_pk_bf16_f32 v2, v4, v5
	v_cvt_pk_bf16_f32 v3, v6, v7
	global_store_dwordx4 v[58:59], v[0:3], off offset:-1024
	s_nop 1
	s_nop 0
	v_pk_mul_f32 v[0:1], v[228:229], v[16:17]
	v_pk_mul_f32 v[2:3], v[230:231], v[10:11]
	v_pk_mul_f32 v[4:5], v[232:233], v[14:15]
	v_pk_mul_f32 v[6:7], v[234:235], v[8:9]
	v_cvt_pk_bf16_f32 v0, v0, v1
	v_cvt_pk_bf16_f32 v1, v2, v3
	v_cvt_pk_bf16_f32 v2, v4, v5
	v_cvt_pk_bf16_f32 v3, v6, v7
	global_store_dwordx4 v[58:59], v[0:3], off
	s_nop 1
	s_cbranch_scc1 .LBB0_1035

; __device__ __forceinline__ float bf_lo(unsigned v) { return __uint_as_float(v << 16); }
; __device__ __forceinline__ float bf_hi(unsigned v) { return __uint_as_float(v & 0xffff0000u); }
; __device__ __forceinline__ void rms_rowb_to_f32(const bf16* hrow, const float* w, float* orow, int lane) {
;     const v4u* hr = (const v4u*)hrow + lane; float v[8][8]; float s = 0.f;
; #pragma unroll
;     for (int j = 0; j < 8; ++j) { const v4u q = hr[64 * j];
;         v[j][0] = bf_lo(q.x); v[j][1] = bf_hi(q.x); v[j][2] = bf_lo(q.y); v[j][3] = bf_hi(q.y); v[j][4] = bf_lo(q.z); v[j][5] = bf_hi(q.z); v[j][6] = bf_lo(q.w); v[j][7] = bf_hi(q.w);
; #pragma unroll
;         for (int e = 0; e < 8; ++e) s += v[j][e] * v[j][e]; }
;     const float r = rsqrtf(wave_sum(s) * (1.f / D) + EPS);
; #pragma unroll
;     for (int j = 0; j < 8; ++j) { const int c = (64 * j + lane) * 8; const f32x4 g0 = *(const f32x4*)(w + c), g1 = *(const f32x4*)(w + c + 4);
;         *(f32x4*)(orow + c) = (f32x4){v[j][0] * r * g0.x, v[j][1] * r * g0.y, v[j][2] * r * g0.z, v[j][3] * r * g0.w};
;         *(f32x4*)(orow + c + 4) = (f32x4){v[j][4] * r * g1.x, v[j][5] * r * g1.y, v[j][6] * r * g1.z, v[j][7] * r * g1.w}; }
.LBB0_1169:
	s_cmp_lt_i32 s30, 13
	s_cselect_b64 s[0:1], -1, 0
	s_and_b64 s[0:1], s[0:1], s[2:3]
	s_and_b64 s[0:1], s[0:1], s[10:11]
	s_andn2_b64 vcc, exec, s[0:1]
	s_cbranch_vccnz .LBB0_1172
	s_waitcnt vmcnt(0)
	v_mbcnt_hi_u32_b32 v0, -1, v168
	v_and_b32_e32 v1, 64, v0
	v_add_u32_e32 v1, 64, v1
	v_xor_b32_e32 v2, 1, v0
	v_cmp_lt_i32_e32 vcc, v2, v1
	v_mov_b32_e32 v145, 0
	s_ashr_i32 s93, s92, 31
	v_cndmask_b32_e32 v2, v0, v2, vcc
	v_lshlrev_b32_e32 v90, 2, v2
	v_xor_b32_e32 v2, 2, v0
	v_cmp_lt_i32_e32 vcc, v2, v1
	s_lshl_b64 s[0:1], s[92:93], 13
	s_add_u32 s0, s28, s0
	v_cndmask_b32_e32 v2, v0, v2, vcc
	v_lshlrev_b32_e32 v91, 2, v2
	v_xor_b32_e32 v2, 4, v0
	v_cmp_lt_i32_e32 vcc, v2, v1
	v_mov_b32_e32 v147, v145
	s_addc_u32 s1, s29, s1
	v_cndmask_b32_e32 v2, v0, v2, vcc
	v_lshlrev_b32_e32 v92, 2, v2
	v_xor_b32_e32 v2, 8, v0
	v_cmp_lt_i32_e32 vcc, v2, v1
	s_ashr_i32 s95, s94, 31
	s_lshl_b64 s[2:3], s[92:93], 14
	v_cndmask_b32_e32 v2, v0, v2, vcc
	v_lshlrev_b32_e32 v93, 2, v2
	v_xor_b32_e32 v2, 16, v0
	v_cmp_lt_i32_e32 vcc, v2, v1
	v_lshl_add_u64 v[8:9], s[24:25], 0, v[144:145]
	s_movk_i32 s4, 0x1000
	v_cndmask_b32_e32 v2, v0, v2, vcc
	v_lshlrev_b32_e32 v94, 2, v2
	v_xor_b32_e32 v2, 32, v0
	v_cmp_lt_i32_e32 vcc, v2, v1
	v_mov_b32_e32 v1, v145
	s_movk_i32 s5, 0x2000
	v_cndmask_b32_e32 v0, v0, v2, vcc
	v_lshlrev_b32_e32 v95, 2, v0
	v_or_b32_e32 v0, 0x1000, v144
	v_lshl_add_u64 v[10:11], s[24:25], 0, v[0:1]
	v_or_b32_e32 v0, 0x1800, v144
	v_lshl_add_u64 v[12:13], s[24:25], 0, v[0:1]
	v_or_b32_e32 v0, 0x2000, v144
	v_lshl_add_u64 v[14:15], s[24:25], 0, v[0:1]
	v_or_b32_e32 v0, 0x2800, v144
	v_lshl_add_u64 v[16:17], s[24:25], 0, v[0:1]
	v_or_b32_e32 v0, 0x3000, v144
	v_lshl_add_u64 v[18:19], s[24:25], 0, v[0:1]
	v_or_b32_e32 v0, 0x3800, v144
	v_lshl_add_u64 v[20:21], s[24:25], 0, v[0:1]
	v_lshl_add_u64 v[0:1], s[0:1], 0, v[146:147]
	s_mov_b64 s[0:1], 0x1c800000
	v_lshl_add_u64 v[22:23], v[0:1], 0, s[0:1]
	s_lshl_b64 s[0:1], s[94:95], 13
	s_add_u32 s2, s26, s2
	s_addc_u32 s3, s27, s3
	s_movk_i32 s6, 0x3000
	v_lshl_add_u64 v[24:25], s[2:3], 0, v[144:145]
	s_lshl_b64 s[2:3], s[94:95], 14
	v_mov_b32_e32 v96, 0x358637bd
	s_mov_b32 s7, 0x800000
	global_load_dwordx4 v[172:175], v[8:9], off offset:16
	global_load_dwordx4 v[176:179], v[8:9], off
	global_load_dwordx4 v[180:183], v[8:9], off offset:2048
	global_load_dwordx4 v[184:187], v[8:9], off offset:2064
	global_load_dwordx4 v[188:191], v[10:11], off
	global_load_dwordx4 v[192:195], v[10:11], off offset:16
	global_load_dwordx4 v[196:199], v[12:13], off
	global_load_dwordx4 v[200:203], v[12:13], off offset:16
	global_load_dwordx4 v[204:207], v[14:15], off
	global_load_dwordx4 v[208:211], v[14:15], off offset:16
	global_load_dwordx4 v[212:215], v[16:17], off
	global_load_dwordx4 v[216:219], v[16:17], off offset:16
	global_load_dwordx4 v[220:223], v[18:19], off
	global_load_dwordx4 v[224:227], v[18:19], off offset:16
	global_load_dwordx4 v[228:231], v[20:21], off
	global_load_dwordx4 v[232:235], v[20:21], off offset:16
.LBB0_1171:
	global_load_dwordx4 v[26:29], v[22:23], off
	global_load_dwordx4 v[30:33], v[22:23], off offset:1024
	global_load_dwordx4 v[34:37], v[22:23], off offset:2048
	global_load_dwordx4 v[38:41], v[22:23], off offset:3072
	v_add_co_u32_e32 v46, vcc, s4, v22
	v_addc_co_u32_e32 v47, vcc, 0, v23, vcc
	global_load_dwordx4 v[42:45], v[46:47], off
	global_load_dwordx4 v[98:101], v[46:47], off offset:1024
	global_load_dwordx4 v[102:105], v[46:47], off offset:2048
	global_load_dwordx4 v[106:109], v[46:47], off offset:3072
	s_add_i32 s92, s92, s94
	v_lshl_add_u64 v[22:23], v[22:23], 0, s[0:1]
	s_cmpk_lt_i32 s92, 0x2000
	s_waitcnt vmcnt(7)
	v_lshlrev_b32_e32 v84, 16, v26
	v_and_b32_e32 v85, 0xffff0000, v26
	v_lshlrev_b32_e32 v88, 16, v27
	v_and_b32_e32 v89, 0xffff0000, v27
	v_pk_mul_f32 v[110:111], v[84:85], v[84:85]
	v_pk_mul_f32 v[112:113], v[88:89], v[88:89]
	v_add_f32_e32 v97, v110, v111
	v_lshlrev_b32_e32 v82, 16, v28
	v_and_b32_e32 v83, 0xffff0000, v28
	v_add_f32_e32 v97, v112, v97
	v_pk_mul_f32 v[114:115], v[82:83], v[82:83]
	v_add_f32_e32 v97, v113, v97
	v_lshlrev_b32_e32 v86, 16, v29
	v_and_b32_e32 v87, 0xffff0000, v29
	v_add_f32_e32 v97, v114, v97
	v_pk_mul_f32 v[116:117], v[86:87], v[86:87]
	v_add_f32_e32 v97, v115, v97
	s_waitcnt vmcnt(6)
	v_lshlrev_b32_e32 v76, 16, v30
	v_and_b32_e32 v77, 0xffff0000, v30
	v_add_f32_e32 v97, v116, v97
	v_pk_mul_f32 v[118:119], v[76:77], v[76:77]
	v_add_f32_e32 v97, v117, v97
	v_lshlrev_b32_e32 v80, 16, v31
	v_and_b32_e32 v81, 0xffff0000, v31
	v_add_f32_e32 v97, v118, v97
	v_pk_mul_f32 v[120:121], v[80:81], v[80:81]
	v_add_f32_e32 v97, v119, v97
	v_lshlrev_b32_e32 v74, 16, v32
	v_and_b32_e32 v75, 0xffff0000, v32
	v_add_f32_e32 v97, v120, v97
	v_pk_mul_f32 v[122:123], v[74:75], v[74:75]
	v_add_f32_e32 v97, v121, v97
	v_lshlrev_b32_e32 v78, 16, v33
	v_and_b32_e32 v79, 0xffff0000, v33
	v_add_f32_e32 v97, v122, v97
	v_pk_mul_f32 v[124:125], v[78:79], v[78:79]
	v_add_f32_e32 v97, v123, v97
	s_waitcnt vmcnt(5)
	v_lshlrev_b32_e32 v50, 16, v34
	v_and_b32_e32 v51, 0xffff0000, v34
	v_add_f32_e32 v97, v124, v97
	v_pk_mul_f32 v[126:127], v[50:51], v[50:51]
	v_add_f32_e32 v97, v125, v97
	v_lshlrev_b32_e32 v66, 16, v35
	v_and_b32_e32 v67, 0xffff0000, v35
	v_add_f32_e32 v97, v126, v97
	v_pk_mul_f32 v[128:129], v[66:67], v[66:67]
	v_add_f32_e32 v97, v127, v97
	v_lshlrev_b32_e32 v64, 16, v36
	v_and_b32_e32 v65, 0xffff0000, v36
	v_add_f32_e32 v97, v128, v97
	v_pk_mul_f32 v[130:131], v[64:65], v[64:65]
	v_add_f32_e32 v97, v129, v97
	v_lshlrev_b32_e32 v72, 16, v37
	v_and_b32_e32 v73, 0xffff0000, v37
	v_add_f32_e32 v97, v130, v97
	v_pk_mul_f32 v[132:133], v[72:73], v[72:73]
	v_add_f32_e32 v97, v131, v97
	s_waitcnt vmcnt(4)
; __device__ __forceinline__ float bf_lo(unsigned v) { return __uint_as_float(v << 16); }
; __device__ __forceinline__ float bf_hi(unsigned v) { return __uint_as_float(v & 0xffff0000u); }
; __device__ __forceinline__ void rms_rowb_to_f32(const bf16* hrow, const float* w, float* orow, int lane) {
;     const v4u* hr = (const v4u*)hrow + lane; float v[8][8]; float s = 0.f;
; #pragma unroll
;     for (int j = 0; j < 8; ++j) { const v4u q = hr[64 * j];
;         v[j][0] = bf_lo(q.x); v[j][1] = bf_hi(q.x); v[j][2] = bf_lo(q.y); v[j][3] = bf_hi(q.y); v[j][4] = bf_lo(q.z); v[j][5] = bf_hi(q.z); v[j][6] = bf_lo(q.w); v[j][7] = bf_hi(q.w);
; #pragma unroll
;         for (int e = 0; e < 8; ++e) s += v[j][e] * v[j][e]; }
;     const float r = rsqrtf(wave_sum(s) * (1.f / D) + EPS);
	v_lshlrev_b32_e32 v48, 16, v38
	v_and_b32_e32 v49, 0xffff0000, v38
	v_add_f32_e32 v97, v132, v97
	v_pk_mul_f32 v[134:135], v[48:49], v[48:49]
	v_add_f32_e32 v97, v133, v97
	v_lshlrev_b32_e32 v60, 16, v39
	v_and_b32_e32 v61, 0xffff0000, v39
	v_add_f32_e32 v97, v134, v97
	v_pk_mul_f32 v[136:137], v[60:61], v[60:61]
	v_add_f32_e32 v97, v135, v97
	v_lshlrev_b32_e32 v46, 16, v40
	v_and_b32_e32 v47, 0xffff0000, v40
	v_add_f32_e32 v97, v136, v97
	v_pk_mul_f32 v[138:139], v[46:47], v[46:47]
	v_add_f32_e32 v97, v137, v97
	v_lshlrev_b32_e32 v56, 16, v41
	v_and_b32_e32 v57, 0xffff0000, v41
	v_add_f32_e32 v97, v138, v97
	v_pk_mul_f32 v[140:141], v[56:57], v[56:57]
	v_add_f32_e32 v97, v139, v97
	s_waitcnt vmcnt(3)
	v_lshlrev_b32_e32 v62, 16, v42
	v_and_b32_e32 v63, 0xffff0000, v42
	v_add_f32_e32 v97, v140, v97
	v_lshlrev_b32_e32 v58, 16, v44
	v_and_b32_e32 v59, 0xffff0000, v44
	v_lshlrev_b32_e32 v68, 16, v45
	v_and_b32_e32 v69, 0xffff0000, v45
	s_waitcnt vmcnt(2)
	v_lshlrev_b32_e32 v44, 16, v98
	v_and_b32_e32 v45, 0xffff0000, v98
	v_lshlrev_b32_e32 v54, 16, v99
	v_and_b32_e32 v55, 0xffff0000, v99
	v_pk_mul_f32 v[98:99], v[62:63], v[62:63]
	v_add_f32_e32 v97, v141, v97
	v_lshlrev_b32_e32 v70, 16, v43
	v_and_b32_e32 v71, 0xffff0000, v43
	v_add_f32_e32 v97, v98, v97
	v_lshlrev_b32_e32 v42, 16, v100
	v_and_b32_e32 v43, 0xffff0000, v100
	v_lshlrev_b32_e32 v52, 16, v101
	v_and_b32_e32 v53, 0xffff0000, v101
	v_pk_mul_f32 v[100:101], v[70:71], v[70:71]
	v_add_f32_e32 v97, v99, v97
	v_add_f32_e32 v97, v100, v97
	s_waitcnt vmcnt(1)
	v_lshlrev_b32_e32 v34, 16, v102
	v_and_b32_e32 v35, 0xffff0000, v102
	v_lshlrev_b32_e32 v38, 16, v103
	v_and_b32_e32 v39, 0xffff0000, v103
	v_pk_mul_f32 v[102:103], v[58:59], v[58:59]
	v_add_f32_e32 v97, v101, v97
	v_add_f32_e32 v97, v102, v97
	v_lshlrev_b32_e32 v36, 16, v104
	v_and_b32_e32 v37, 0xffff0000, v104
	v_lshlrev_b32_e32 v40, 16, v105
	v_and_b32_e32 v41, 0xffff0000, v105
	v_pk_mul_f32 v[104:105], v[68:69], v[68:69]
	v_add_f32_e32 v97, v103, v97
	v_add_f32_e32 v97, v104, v97
	s_waitcnt vmcnt(0)
	v_lshlrev_b32_e32 v26, 16, v106
	v_and_b32_e32 v27, 0xffff0000, v106
	v_lshlrev_b32_e32 v28, 16, v107
	v_and_b32_e32 v29, 0xffff0000, v107
	v_pk_mul_f32 v[106:107], v[44:45], v[44:45]
	v_add_f32_e32 v97, v105, v97
	v_add_f32_e32 v97, v106, v97
	v_lshlrev_b32_e32 v30, 16, v108
	v_and_b32_e32 v31, 0xffff0000, v108
	v_lshlrev_b32_e32 v32, 16, v109
	v_and_b32_e32 v33, 0xffff0000, v109
	v_pk_mul_f32 v[108:109], v[54:55], v[54:55]
	v_add_f32_e32 v97, v107, v97
	v_add_f32_e32 v97, v108, v97
	v_pk_mul_f32 v[110:111], v[42:43], v[42:43]
	v_add_f32_e32 v97, v109, v97
	v_add_f32_e32 v97, v110, v97
	v_pk_mul_f32 v[142:143], v[52:53], v[52:53]
	v_add_f32_e32 v97, v111, v97
	v_add_f32_e32 v97, v142, v97
	v_pk_mul_f32 v[144:145], v[34:35], v[34:35]
	v_add_f32_e32 v97, v143, v97
	v_add_f32_e32 v97, v144, v97
	v_pk_mul_f32 v[146:147], v[38:39], v[38:39]
	v_add_f32_e32 v97, v145, v97
	v_add_f32_e32 v97, v146, v97
	v_pk_mul_f32 v[148:149], v[36:37], v[36:37]
	v_add_f32_e32 v97, v147, v97
	v_add_f32_e32 v97, v148, v97
	v_pk_mul_f32 v[150:151], v[40:41], v[40:41]
	v_add_f32_e32 v97, v149, v97
	v_add_f32_e32 v97, v150, v97
	v_pk_mul_f32 v[152:153], v[26:27], v[26:27]
	v_add_f32_e32 v97, v151, v97
	v_add_f32_e32 v97, v152, v97
	v_pk_mul_f32 v[154:155], v[28:29], v[28:29]
	v_add_f32_e32 v97, v153, v97
	v_add_f32_e32 v97, v154, v97
	v_pk_mul_f32 v[156:157], v[30:31], v[30:31]
	v_add_f32_e32 v97, v155, v97
	v_add_f32_e32 v97, v156, v97
	v_pk_mul_f32 v[158:159], v[32:33], v[32:33]
	v_add_f32_e32 v97, v157, v97
	v_add_f32_e32 v97, v158, v97
	v_add_f32_e32 v97, v159, v97
	ds_bpermute_b32 v98, v90, v97
	s_waitcnt lgkmcnt(0)
	v_add_f32_e32 v97, v97, v98
	ds_bpermute_b32 v98, v91, v97
	s_waitcnt lgkmcnt(0)
	v_add_f32_e32 v97, v97, v98
	ds_bpermute_b32 v98, v92, v97
	s_waitcnt lgkmcnt(0)
	v_add_f32_e32 v97, v97, v98
	ds_bpermute_b32 v98, v93, v97
	s_waitcnt lgkmcnt(0)
	v_add_f32_e32 v97, v97, v98
	ds_bpermute_b32 v98, v94, v97
	s_waitcnt lgkmcnt(0)
	v_add_f32_e32 v97, v97, v98
	ds_bpermute_b32 v98, v95, v97
	s_waitcnt lgkmcnt(0)
; __device__ __forceinline__ void rms_rowb_to_f32(const bf16* hrow, const float* w, float* orow, int lane) {
;     ...
;     const float r = rsqrtf(wave_sum(s) * (1.f / D) + EPS);
; #pragma unroll
;     for (int j = 0; j < 8; ++j) { const int c = (64 * j + lane) * 8; const f32x4 g0 = *(const f32x4*)(w + c), g1 = *(const f32x4*)(w + c + 4);
;         *(f32x4*)(orow + c) = (f32x4){v[j][0] * r * g0.x, v[j][1] * r * g0.y, v[j][2] * r * g0.z, v[j][3] * r * g0.w};
;         *(f32x4*)(orow + c + 4) = (f32x4){v[j][4] * r * g1.x, v[j][5] * r * g1.y, v[j][6] * r * g1.z, v[j][7] * r * g1.w}; }
	v_add_f32_e32 v97, v97, v98
	v_fmamk_f32 v97, v97, 0x39800000, v96
	v_mul_f32_e32 v98, 0x4b800000, v97
	v_cmp_gt_f32_e32 vcc, s7, v97
	s_nop 1
	v_cndmask_b32_e32 v97, v97, v98, vcc
	v_rsq_f32_e32 v97, v97
	s_nop 0
	v_mul_f32_e32 v98, 0x45800000, v97
	v_cndmask_b32_e32 v98, v97, v98, vcc
	v_pk_mul_f32 v[84:85], v[98:99], v[84:85] op_sel_hi:[0,1]
	v_pk_mul_f32 v[88:89], v[98:99], v[88:89] op_sel_hi:[0,1]
	v_pk_mul_f32 v[82:83], v[98:99], v[82:83] op_sel_hi:[0,1]
	v_pk_mul_f32 v[86:87], v[98:99], v[86:87] op_sel_hi:[0,1]
	v_pk_mul_f32 v[6:7], v[178:179], v[88:89]
	v_pk_mul_f32 v[4:5], v[176:177], v[84:85]
	v_pk_mul_f32 v[2:3], v[174:175], v[86:87]
	v_pk_mul_f32 v[0:1], v[172:173], v[82:83]
	global_store_dwordx4 v[24:25], v[4:7], off
	global_store_dwordx4 v[24:25], v[0:3], off offset:16
	s_nop 1
	s_nop 0
	v_pk_mul_f32 v[80:81], v[98:99], v[80:81] op_sel_hi:[0,1]
	v_pk_mul_f32 v[76:77], v[98:99], v[76:77] op_sel_hi:[0,1]
	v_pk_mul_f32 v[78:79], v[98:99], v[78:79] op_sel_hi:[0,1]
	v_pk_mul_f32 v[74:75], v[98:99], v[74:75] op_sel_hi:[0,1]
	v_pk_mul_f32 v[66:67], v[98:99], v[66:67] op_sel_hi:[0,1]
	v_pk_mul_f32 v[50:51], v[98:99], v[50:51] op_sel_hi:[0,1]
	v_pk_mul_f32 v[72:73], v[98:99], v[72:73] op_sel_hi:[0,1]
	v_pk_mul_f32 v[64:65], v[98:99], v[64:65] op_sel_hi:[0,1]
	v_pk_mul_f32 v[48:49], v[98:99], v[48:49] op_sel_hi:[0,1]
	v_pk_mul_f32 v[56:57], v[98:99], v[56:57] op_sel_hi:[0,1]
	v_pk_mul_f32 v[46:47], v[98:99], v[46:47] op_sel_hi:[0,1]
	v_pk_mul_f32 v[44:45], v[98:99], v[44:45] op_sel_hi:[0,1]
	v_pk_mul_f32 v[42:43], v[98:99], v[42:43] op_sel_hi:[0,1]
	v_pk_mul_f32 v[38:39], v[98:99], v[38:39] op_sel_hi:[0,1]
	v_pk_mul_f32 v[34:35], v[98:99], v[34:35] op_sel_hi:[0,1]
	v_pk_mul_f32 v[40:41], v[98:99], v[40:41] op_sel_hi:[0,1]
	v_pk_mul_f32 v[36:37], v[98:99], v[36:37] op_sel_hi:[0,1]
	v_pk_mul_f32 v[28:29], v[98:99], v[28:29] op_sel_hi:[0,1]
	v_pk_mul_f32 v[26:27], v[98:99], v[26:27] op_sel_hi:[0,1]
	v_pk_mul_f32 v[32:33], v[98:99], v[32:33] op_sel_hi:[0,1]
	v_pk_mul_f32 v[30:31], v[98:99], v[30:31] op_sel_hi:[0,1]
	v_pk_mul_f32 v[0:1], v[180:181], v[76:77]
	v_pk_mul_f32 v[2:3], v[182:183], v[80:81]
	v_pk_mul_f32 v[4:5], v[184:185], v[74:75]
	v_pk_mul_f32 v[6:7], v[186:187], v[78:79]
	global_store_dwordx4 v[24:25], v[0:3], off offset:2048
	global_store_dwordx4 v[24:25], v[4:7], off offset:2064
	s_nop 1
	s_nop 0
	v_add_co_u32_e32 v74, vcc, s4, v24
	v_pk_mul_f32 v[0:1], v[188:189], v[50:51]
	v_addc_co_u32_e32 v75, vcc, 0, v25, vcc
	v_add_co_u32_e32 v76, vcc, s5, v24
	v_pk_mul_f32 v[2:3], v[190:191], v[66:67]
	s_nop 0
	v_addc_co_u32_e32 v77, vcc, 0, v25, vcc
	v_pk_mul_f32 v[4:5], v[192:193], v[64:65]
	v_pk_mul_f32 v[6:7], v[194:195], v[72:73]
	global_store_dwordx4 v[76:77], v[0:3], off offset:-4096
	global_store_dwordx4 v[74:75], v[4:7], off offset:16
	s_nop 1
	s_nop 0
	v_pk_mul_f32 v[50:51], v[98:99], v[60:61] op_sel_hi:[0,1]
	v_pk_mul_f32 v[0:1], v[196:197], v[48:49]
	v_pk_mul_f32 v[2:3], v[198:199], v[50:51]
	v_pk_mul_f32 v[4:5], v[200:201], v[46:47]
	v_pk_mul_f32 v[6:7], v[202:203], v[56:57]
	global_store_dwordx4 v[74:75], v[0:3], off offset:2048
	global_store_dwordx4 v[74:75], v[4:7], off offset:2064
	s_nop 1
	s_nop 0
	v_pk_mul_f32 v[46:47], v[98:99], v[70:71] op_sel_hi:[0,1]
	v_pk_mul_f32 v[48:49], v[98:99], v[62:63] op_sel_hi:[0,1]
	v_pk_mul_f32 v[50:51], v[98:99], v[68:69] op_sel_hi:[0,1]
	v_pk_mul_f32 v[56:57], v[98:99], v[58:59] op_sel_hi:[0,1]
	v_pk_mul_f32 v[0:1], v[204:205], v[48:49]
	v_pk_mul_f32 v[2:3], v[206:207], v[46:47]
	v_pk_mul_f32 v[4:5], v[208:209], v[56:57]
	v_pk_mul_f32 v[6:7], v[210:211], v[50:51]
	global_store_dwordx4 v[76:77], v[0:3], off
	global_store_dwordx4 v[76:77], v[4:7], off offset:16
	s_nop 1
	s_nop 0
	v_pk_mul_f32 v[46:47], v[98:99], v[54:55] op_sel_hi:[0,1]
	v_pk_mul_f32 v[48:49], v[98:99], v[52:53] op_sel_hi:[0,1]
	v_pk_mul_f32 v[0:1], v[212:213], v[44:45]
	v_pk_mul_f32 v[2:3], v[214:215], v[46:47]
	v_pk_mul_f32 v[4:5], v[216:217], v[42:43]
	v_pk_mul_f32 v[6:7], v[218:219], v[48:49]
	global_store_dwordx4 v[76:77], v[0:3], off offset:2048
	global_store_dwordx4 v[76:77], v[4:7], off offset:2064
	s_nop 1
	s_nop 0
	v_add_co_u32_e32 v42, vcc, s6, v24
	v_pk_mul_f32 v[0:1], v[220:221], v[34:35]
	v_addc_co_u32_e32 v43, vcc, 0, v25, vcc
	v_pk_mul_f32 v[2:3], v[222:223], v[38:39]
	v_pk_mul_f32 v[4:5], v[224:225], v[36:37]
	v_pk_mul_f32 v[6:7], v[226:227], v[40:41]
	global_store_dwordx4 v[42:43], v[0:3], off
	global_store_dwordx4 v[42:43], v[4:7], off offset:16
	s_nop 1
	s_nop 0
	v_lshl_add_u64 v[24:25], v[24:25], 0, s[2:3]
	v_pk_mul_f32 v[0:1], v[228:229], v[26:27]
	v_pk_mul_f32 v[2:3], v[230:231], v[28:29]
	v_pk_mul_f32 v[4:5], v[232:233], v[30:31]
	v_pk_mul_f32 v[6:7], v[234:235], v[32:33]
	global_store_dwordx4 v[42:43], v[0:3], off offset:2048
	global_store_dwordx4 v[42:43], v[4:7], off offset:2064
	s_nop 1
	s_cbranch_scc1 .LBB0_1171
